# combo2 + mid-phase s_setprio 0/1 flips removed inside each 32-MFMA phase
# baseline (speedup 1.0000x reference)
; #define PG8_STAGE(bufoff, gbase, voff) do { _Pragma("unroll") for (int _i = 0; _i < 2; ++_i) \
;         __builtin_amdgcn_global_load_lds((const unsigned*)((const char*)(gbase) + (voff)[_i]), (PG8_LAS unsigned*)(lds + (bufoff) + ldsw + _i * 8192), 16, 0, 0); } while (0)
; #define PG8_LDA(dst, b, h) do { _Pragma("unroll") for (int m = 0; m < 4; ++m) _Pragma("unroll") for (int k = 0; k < 2; ++k) dst[m][k] = *(const PG8_LAS bf16x8*)(lds + PG8_SA(b, h) + aoff + m * 2048 + k * 1024); } while (0)
; #define PG8_LDB(dst, b, h) do { _Pragma("unroll") for (int n = 0; n < 2; ++n) _Pragma("unroll") for (int k = 0; k < 2; ++k) dst[n][k] = *(const PG8_LAS bf16x8*)(lds + PG8_SB(b, h) + boff + n * 2048 + k * 1024); } while (0)
; #define PG8_MMA(ai, bj, At, Bt) do { __builtin_amdgcn_s_setprio(1); _Pragma("unroll") for (int m = 0; m < 4; ++m) _Pragma("unroll") for (int n = 0; n < 2; ++n) _Pragma("unroll") for (int k = 0; k < 2; ++k) \
;         acc[ai][bj][m][n] = __builtin_amdgcn_mfma_f32_16x16x32_bf16(Bt[n][k], At[m][k], acc[ai][bj][m][n], 0, 0, 0); __builtin_amdgcn_s_setprio(0); } while (0)
; #define PG8_WAIT_V(n) asm volatile("s_waitcnt vmcnt(" #n ")" ::: "memory")
; #define PG8_WAIT_L(n) asm volatile("s_waitcnt lgkmcnt(" #n ")" ::: "memory")
; template <class Epi, class Sched, bool ALIGN_EPI = false, bool SP2 = false>
; __device__ __forceinline__ void gemm_phase(PG8_LAS unsigned char* lds, const Gemm g, const Sched& S, const Epi& E, const int tid) {
;     ...
;             const char* a2 = last ? nA : cA + (size_t)(t + 2) * kstep; const char* b2 = last ? nB : cB + (size_t)(t + 2) * kstep;
;             const char* a3 = a2 + kstep; const char* b3 = b2 + kstep;
;             if (last && has_next) S.a_ready(nxt);
;             if (last) E.prefetch(lds + EPI_LDS_OFF + wid * 1024, cur, wr, wc, lane);
;             if constexpr (SP2) {
;             PG8_LDB(B0, 0, 0); PG8_LDB(B1, 0, 1); PG8_SCHED; PG8_LDA(At, 0, 0); PG8_STAGE(PG8_SA(1, 1), a1 + hstep, voffA);
;             PG8_WAIT_V(8); PG8_WAIT_L(0); PG8_BAR; PG8_MMA(0, 0, At, B0); PG8_MMA(0, 1, At, B1); PG8_BAR; PG8_SCHED;
;             PG8_LDA(At, 0, 1); PG8_STAGE(PG8_SB(0, 0), b2, voffB); PG8_STAGE(PG8_SB(0, 1), b2 + hstep, voffB); PG8_STAGE(PG8_SA(0, 0), a2, voffA);
;             PG8_WAIT_V(8); PG8_WAIT_L(0); PG8_BAR; PG8_MMA(1, 0, At, B0); PG8_MMA(1, 1, At, B1); PG8_BAR; PG8_SCHED;
.LBB0_42:
	s_add_u32 s18, s16, 0x100
	s_addc_u32 s19, s17, 0
	s_and_b64 s[20:21], s[20:21], exec
	s_cselect_b32 s23, s9, s19
	s_cselect_b32 s22, s8, s18
	s_cselect_b32 s21, s15, s74
	s_cselect_b32 s20, s14, s55
	s_add_i32 s3, 0, 0x10000
	s_add_i32 s42, 0, 0x14000
	v_add_u32_e32 v146, s3, v224
	v_add_u32_e32 v162, s42, v224
	ds_read_b128 v[134:137], v146
	ds_read_b128 v[138:141], v146 offset:1024
	ds_read_b128 v[142:145], v146 offset:2048
	ds_read_b128 v[146:149], v146 offset:3072
	ds_read_b128 v[150:153], v162
	ds_read_b128 v[154:157], v162 offset:1024
	ds_read_b128 v[158:161], v162 offset:2048
	ds_read_b128 v[172:175], v162 offset:3072
	v_lshl_add_u64 v[162:163], s[16:17], 0, v[168:169]
	s_add_i32 m0, s27, 0xc000
	ds_read_b128 v[176:179], v228
	ds_read_b128 v[180:183], v228 offset:1024
	ds_read_b128 v[186:189], v228 offset:2048
	ds_read_b128 v[190:193], v228 offset:3072
	ds_read_b128 v[194:197], v228 offset:4096
	ds_read_b128 v[198:201], v228 offset:5120
	ds_read_b128 v[202:205], v228 offset:6144
	ds_read_b128 v[206:209], v228 offset:7168
	global_load_lds_dwordx4 v[162:163], off
	v_lshl_add_u64 v[162:163], s[16:17], 0, v[170:171]
	s_add_i32 m0, s27, 0xe000
	s_nop 0
	global_load_lds_dwordx4 v[162:163], off
	s_waitcnt vmcnt(8)
	s_waitcnt lgkmcnt(0)
	s_setprio 1
	s_barrier
	v_mfma_f32_16x16x32_bf16 v[128:131], v[134:137], v[176:179], v[128:131]
	v_mfma_f32_16x16x32_bf16 v[124:127], v[142:145], v[176:179], v[124:127]
	v_mfma_f32_16x16x32_bf16 v[112:115], v[134:137], v[186:189], v[112:115]
	v_mfma_f32_16x16x32_bf16 v[108:111], v[142:145], v[186:189], v[108:111]
	v_mfma_f32_16x16x32_bf16 v[96:99], v[134:137], v[194:197], v[96:99]
	v_mfma_f32_16x16x32_bf16 v[92:95], v[142:145], v[194:197], v[92:95]
	v_mfma_f32_16x16x32_bf16 v[80:83], v[134:137], v[202:205], v[80:83]
	v_mfma_f32_16x16x32_bf16 v[76:79], v[142:145], v[202:205], v[76:79]
	v_mfma_f32_16x16x32_bf16 v[128:131], v[138:141], v[180:183], v[128:131]
	v_mfma_f32_16x16x32_bf16 v[124:127], v[146:149], v[180:183], v[124:127]
	v_mfma_f32_16x16x32_bf16 v[112:115], v[138:141], v[190:193], v[112:115]
	v_mfma_f32_16x16x32_bf16 v[108:111], v[146:149], v[190:193], v[108:111]
	v_mfma_f32_16x16x32_bf16 v[96:99], v[138:141], v[198:201], v[96:99]
	v_mfma_f32_16x16x32_bf16 v[92:95], v[146:149], v[198:201], v[92:95]
	v_mfma_f32_16x16x32_bf16 v[80:83], v[138:141], v[206:209], v[80:83]
	v_mfma_f32_16x16x32_bf16 v[76:79], v[146:149], v[206:209], v[76:79]
	v_mfma_f32_16x16x32_bf16 v[120:123], v[150:153], v[176:179], v[120:123]
	v_mfma_f32_16x16x32_bf16 v[116:119], v[158:161], v[176:179], v[116:119]
	v_mfma_f32_16x16x32_bf16 v[104:107], v[150:153], v[186:189], v[104:107]
	v_mfma_f32_16x16x32_bf16 v[100:103], v[158:161], v[186:189], v[100:103]
	v_mfma_f32_16x16x32_bf16 v[88:91], v[150:153], v[194:197], v[88:91]
	v_mfma_f32_16x16x32_bf16 v[84:87], v[158:161], v[194:197], v[84:87]
	v_mfma_f32_16x16x32_bf16 v[72:75], v[150:153], v[202:205], v[72:75]
	v_mfma_f32_16x16x32_bf16 v[68:71], v[158:161], v[202:205], v[68:71]
	v_mfma_f32_16x16x32_bf16 v[120:123], v[154:157], v[180:183], v[120:123]
	v_mfma_f32_16x16x32_bf16 v[116:119], v[172:175], v[180:183], v[116:119]
	v_mfma_f32_16x16x32_bf16 v[104:107], v[154:157], v[190:193], v[104:107]
	v_mfma_f32_16x16x32_bf16 v[100:103], v[172:175], v[190:193], v[100:103]
	v_mfma_f32_16x16x32_bf16 v[88:91], v[154:157], v[198:201], v[88:91]
	v_mfma_f32_16x16x32_bf16 v[84:87], v[172:175], v[198:201], v[84:87]
	v_mfma_f32_16x16x32_bf16 v[72:75], v[154:157], v[206:209], v[72:75]
	v_mfma_f32_16x16x32_bf16 v[68:71], v[172:175], v[206:209], v[68:71]
	s_setprio 0
	s_barrier
	s_add_i32 s3, s3, s26
	v_lshl_add_u64 v[162:163], s[20:21], 0, v[2:3]
	s_mov_b32 m0, s3
	ds_read_b128 v[176:179], v228 offset:16384
	ds_read_b128 v[180:183], v228 offset:17408
	ds_read_b128 v[186:189], v228 offset:18432
	ds_read_b128 v[190:193], v228 offset:19456
	ds_read_b128 v[194:197], v228 offset:20480
	ds_read_b128 v[198:201], v228 offset:21504
	ds_read_b128 v[202:205], v228 offset:22528
	ds_read_b128 v[206:209], v228 offset:23552
	global_load_lds_dwordx4 v[162:163], off
	s_add_i32 m0, s3, 0x2000
	s_add_u32 s16, s20, 0x160000
	v_lshl_add_u64 v[210:211], s[20:21], 0, v[166:167]
	s_addc_u32 s17, s21, 0
	s_add_i32 s3, s42, s26
	global_load_lds_dwordx4 v[210:211], off
	v_lshl_add_u64 v[212:213], s[16:17], 0, v[2:3]
	s_mov_b32 m0, s3
	v_lshl_add_u64 v[214:215], s[22:23], 0, v[164:165]
	global_load_lds_dwordx4 v[212:213], off
	v_lshl_add_u64 v[212:213], s[16:17], 0, v[166:167]
	s_add_i32 m0, s3, 0x2000
	s_nop 0
	global_load_lds_dwordx4 v[212:213], off
	v_lshl_add_u64 v[212:213], s[22:23], 0, v[0:1]
	s_mov_b32 m0, s27
	s_nop 0
	global_load_lds_dwordx4 v[212:213], off
	s_mov_b32 m0, s28
	s_nop 0
	global_load_lds_dwordx4 v[214:215], off
	s_waitcnt vmcnt(8)
	s_waitcnt lgkmcnt(0)
	s_setprio 1
	s_barrier
; #define PG8_STAGE(bufoff, gbase, voff) do { _Pragma("unroll") for (int _i = 0; _i < 2; ++_i) \
;         __builtin_amdgcn_global_load_lds((const unsigned*)((const char*)(gbase) + (voff)[_i]), (PG8_LAS unsigned*)(lds + (bufoff) + ldsw + _i * 8192), 16, 0, 0); } while (0)
; #define PG8_LDA(dst, b, h) do { _Pragma("unroll") for (int m = 0; m < 4; ++m) _Pragma("unroll") for (int k = 0; k < 2; ++k) dst[m][k] = *(const PG8_LAS bf16x8*)(lds + PG8_SA(b, h) + aoff + m * 2048 + k * 1024); } while (0)
; #define PG8_LDB(dst, b, h) do { _Pragma("unroll") for (int n = 0; n < 2; ++n) _Pragma("unroll") for (int k = 0; k < 2; ++k) dst[n][k] = *(const PG8_LAS bf16x8*)(lds + PG8_SB(b, h) + boff + n * 2048 + k * 1024); } while (0)
; #define PG8_MMA(ai, bj, At, Bt) do { __builtin_amdgcn_s_setprio(1); _Pragma("unroll") for (int m = 0; m < 4; ++m) _Pragma("unroll") for (int n = 0; n < 2; ++n) _Pragma("unroll") for (int k = 0; k < 2; ++k) \
;         acc[ai][bj][m][n] = __builtin_amdgcn_mfma_f32_16x16x32_bf16(Bt[n][k], At[m][k], acc[ai][bj][m][n], 0, 0, 0); __builtin_amdgcn_s_setprio(0); } while (0)
; #define PG8_WAIT_V(n) asm volatile("s_waitcnt vmcnt(" #n ")" ::: "memory")
; #define PG8_WAIT_L(n) asm volatile("s_waitcnt lgkmcnt(" #n ")" ::: "memory")
; #define PG8_BAR __builtin_amdgcn_s_barrier()
; #define PG8_SCHED __builtin_amdgcn_sched_barrier(0)
; template <class Epi, class Sched, bool ALIGN_EPI = false, bool SP2 = false>
; __device__ __forceinline__ void gemm_phase(PG8_LAS unsigned char* lds, const Gemm g, const Sched& S, const Epi& E, const int tid) {
;     ...
;             PG8_WAIT_V(8); PG8_WAIT_L(0); PG8_BAR; PG8_MMA(1, 0, At, B0); PG8_MMA(1, 1, At, B1); PG8_BAR; PG8_SCHED;
;             PG8_LDB(B0, 1, 0); PG8_LDB(B1, 1, 1); PG8_SCHED; PG8_LDA(At, 1, 0); PG8_STAGE(PG8_SA(0, 1), a2 + hstep, voffA);
;             PG8_WAIT_V(8); PG8_WAIT_L(0); PG8_BAR; PG8_MMA(0, 0, At, B0); PG8_MMA(0, 1, At, B1); PG8_BAR; PG8_SCHED;
	v_mfma_f32_16x16x32_bf16 v[64:67], v[134:137], v[176:179], v[64:67]
	v_mfma_f32_16x16x32_bf16 v[60:63], v[142:145], v[176:179], v[60:63]
	v_mfma_f32_16x16x32_bf16 v[48:51], v[134:137], v[186:189], v[48:51]
	v_mfma_f32_16x16x32_bf16 v[44:47], v[142:145], v[186:189], v[44:47]
	v_mfma_f32_16x16x32_bf16 v[32:35], v[134:137], v[194:197], v[32:35]
	v_mfma_f32_16x16x32_bf16 v[28:31], v[142:145], v[194:197], v[28:31]
	v_mfma_f32_16x16x32_bf16 v[16:19], v[134:137], v[202:205], v[16:19]
	v_mfma_f32_16x16x32_bf16 v[12:15], v[142:145], v[202:205], v[12:15]
	v_mfma_f32_16x16x32_bf16 v[64:67], v[138:141], v[180:183], v[64:67]
	v_mfma_f32_16x16x32_bf16 v[60:63], v[146:149], v[180:183], v[60:63]
	v_mfma_f32_16x16x32_bf16 v[48:51], v[138:141], v[190:193], v[48:51]
	v_mfma_f32_16x16x32_bf16 v[44:47], v[146:149], v[190:193], v[44:47]
	v_mfma_f32_16x16x32_bf16 v[32:35], v[138:141], v[198:201], v[32:35]
	v_mfma_f32_16x16x32_bf16 v[28:31], v[146:149], v[198:201], v[28:31]
	v_mfma_f32_16x16x32_bf16 v[16:19], v[138:141], v[206:209], v[16:19]
	v_mfma_f32_16x16x32_bf16 v[12:15], v[146:149], v[206:209], v[12:15]
	v_mfma_f32_16x16x32_bf16 v[56:59], v[150:153], v[176:179], v[56:59]
	v_mfma_f32_16x16x32_bf16 v[52:55], v[158:161], v[176:179], v[52:55]
	v_mfma_f32_16x16x32_bf16 v[40:43], v[150:153], v[186:189], v[40:43]
	v_mfma_f32_16x16x32_bf16 v[36:39], v[158:161], v[186:189], v[36:39]
	v_mfma_f32_16x16x32_bf16 v[24:27], v[150:153], v[194:197], v[24:27]
	v_mfma_f32_16x16x32_bf16 v[20:23], v[158:161], v[194:197], v[20:23]
	v_mfma_f32_16x16x32_bf16 v[8:11], v[150:153], v[202:205], v[8:11]
	v_mfma_f32_16x16x32_bf16 v[4:7], v[158:161], v[202:205], v[4:7]
	v_mfma_f32_16x16x32_bf16 v[56:59], v[154:157], v[180:183], v[56:59]
	v_mfma_f32_16x16x32_bf16 v[52:55], v[172:175], v[180:183], v[52:55]
	v_mfma_f32_16x16x32_bf16 v[40:43], v[154:157], v[190:193], v[40:43]
	v_mfma_f32_16x16x32_bf16 v[36:39], v[172:175], v[190:193], v[36:39]
	v_mfma_f32_16x16x32_bf16 v[24:27], v[154:157], v[198:201], v[24:27]
	v_mfma_f32_16x16x32_bf16 v[20:23], v[172:175], v[198:201], v[20:23]
	v_mfma_f32_16x16x32_bf16 v[8:11], v[154:157], v[206:209], v[8:11]
	v_mfma_f32_16x16x32_bf16 v[4:7], v[172:175], v[206:209], v[4:7]
	s_setprio 0
	s_barrier
	s_add_i32 s3, 0, 0x18000
	s_add_i32 s42, 0, 0x1c000
	v_add_u32_e32 v146, s3, v224
	v_add_u32_e32 v172, s42, v224
	ds_read_b128 v[134:137], v146
	ds_read_b128 v[138:141], v146 offset:1024
	ds_read_b128 v[142:145], v146 offset:2048
	ds_read_b128 v[146:149], v146 offset:3072
	ds_read_b128 v[150:153], v172
	ds_read_b128 v[154:157], v172 offset:1024
	ds_read_b128 v[158:161], v172 offset:2048
	ds_read_b128 v[172:175], v172 offset:3072
	s_add_u32 s16, s22, 0x160000
	s_addc_u32 s17, s23, 0
	s_mov_b32 m0, s29
	v_lshl_add_u64 v[216:217], s[16:17], 0, v[0:1]
	ds_read_b128 v[176:179], v228 offset:32768
	ds_read_b128 v[180:183], v228 offset:33792
	ds_read_b128 v[186:189], v228 offset:34816
	ds_read_b128 v[190:193], v228 offset:35840
	ds_read_b128 v[194:197], v228 offset:36864
	ds_read_b128 v[198:201], v228 offset:37888
	ds_read_b128 v[202:205], v228 offset:38912
	ds_read_b128 v[206:209], v228 offset:39936
	global_load_lds_dwordx4 v[216:217], off
	v_lshl_add_u64 v[216:217], s[16:17], 0, v[164:165]
	s_mov_b32 m0, s30
	s_nop 0
	global_load_lds_dwordx4 v[216:217], off
	s_waitcnt vmcnt(8)
	s_waitcnt lgkmcnt(0)
	s_setprio 1
	s_barrier
	v_mfma_f32_16x16x32_bf16 v[128:131], v[134:137], v[176:179], v[128:131]
	v_mfma_f32_16x16x32_bf16 v[124:127], v[142:145], v[176:179], v[124:127]
	v_mfma_f32_16x16x32_bf16 v[112:115], v[134:137], v[186:189], v[112:115]
	v_mfma_f32_16x16x32_bf16 v[108:111], v[142:145], v[186:189], v[108:111]
	v_mfma_f32_16x16x32_bf16 v[96:99], v[134:137], v[194:197], v[96:99]
	v_mfma_f32_16x16x32_bf16 v[92:95], v[142:145], v[194:197], v[92:95]
	v_mfma_f32_16x16x32_bf16 v[80:83], v[134:137], v[202:205], v[80:83]
	v_mfma_f32_16x16x32_bf16 v[76:79], v[142:145], v[202:205], v[76:79]
	v_mfma_f32_16x16x32_bf16 v[128:131], v[138:141], v[180:183], v[128:131]
	v_mfma_f32_16x16x32_bf16 v[124:127], v[146:149], v[180:183], v[124:127]
	v_mfma_f32_16x16x32_bf16 v[112:115], v[138:141], v[190:193], v[112:115]
	v_mfma_f32_16x16x32_bf16 v[108:111], v[146:149], v[190:193], v[108:111]
	v_mfma_f32_16x16x32_bf16 v[96:99], v[138:141], v[198:201], v[96:99]
	v_mfma_f32_16x16x32_bf16 v[92:95], v[146:149], v[198:201], v[92:95]
	v_mfma_f32_16x16x32_bf16 v[80:83], v[138:141], v[206:209], v[80:83]
	v_mfma_f32_16x16x32_bf16 v[76:79], v[146:149], v[206:209], v[76:79]
	v_mfma_f32_16x16x32_bf16 v[120:123], v[150:153], v[176:179], v[120:123]
	v_mfma_f32_16x16x32_bf16 v[116:119], v[158:161], v[176:179], v[116:119]
	v_mfma_f32_16x16x32_bf16 v[104:107], v[150:153], v[186:189], v[104:107]
	v_mfma_f32_16x16x32_bf16 v[100:103], v[158:161], v[186:189], v[100:103]
	v_mfma_f32_16x16x32_bf16 v[88:91], v[150:153], v[194:197], v[88:91]
	v_mfma_f32_16x16x32_bf16 v[84:87], v[158:161], v[194:197], v[84:87]
	v_mfma_f32_16x16x32_bf16 v[72:75], v[150:153], v[202:205], v[72:75]
	v_mfma_f32_16x16x32_bf16 v[68:71], v[158:161], v[202:205], v[68:71]
	v_mfma_f32_16x16x32_bf16 v[120:123], v[154:157], v[180:183], v[120:123]
	v_mfma_f32_16x16x32_bf16 v[116:119], v[172:175], v[180:183], v[116:119]
	v_mfma_f32_16x16x32_bf16 v[104:107], v[154:157], v[190:193], v[104:107]
	v_mfma_f32_16x16x32_bf16 v[100:103], v[172:175], v[190:193], v[100:103]
	v_mfma_f32_16x16x32_bf16 v[88:91], v[154:157], v[198:201], v[88:91]
	v_mfma_f32_16x16x32_bf16 v[84:87], v[172:175], v[198:201], v[84:87]
	v_mfma_f32_16x16x32_bf16 v[72:75], v[154:157], v[206:209], v[72:75]
	v_mfma_f32_16x16x32_bf16 v[68:71], v[172:175], v[206:209], v[68:71]
	s_setprio 0
	s_barrier
; #define PG8_STAGE(bufoff, gbase, voff) do { _Pragma("unroll") for (int _i = 0; _i < 2; ++_i) \
;         __builtin_amdgcn_global_load_lds((const unsigned*)((const char*)(gbase) + (voff)[_i]), (PG8_LAS unsigned*)(lds + (bufoff) + ldsw + _i * 8192), 16, 0, 0); } while (0)
; #define PG8_LDA(dst, b, h) do { _Pragma("unroll") for (int m = 0; m < 4; ++m) _Pragma("unroll") for (int k = 0; k < 2; ++k) dst[m][k] = *(const PG8_LAS bf16x8*)(lds + PG8_SA(b, h) + aoff + m * 2048 + k * 1024); } while (0)
; #define PG8_MMA(ai, bj, At, Bt) do { __builtin_amdgcn_s_setprio(1); _Pragma("unroll") for (int m = 0; m < 4; ++m) _Pragma("unroll") for (int n = 0; n < 2; ++n) _Pragma("unroll") for (int k = 0; k < 2; ++k) \
;         acc[ai][bj][m][n] = __builtin_amdgcn_mfma_f32_16x16x32_bf16(Bt[n][k], At[m][k], acc[ai][bj][m][n], 0, 0, 0); __builtin_amdgcn_s_setprio(0); } while (0)
; #define PG8_WAIT_V(n) asm volatile("s_waitcnt vmcnt(" #n ")" ::: "memory")
; #define PG8_WAIT_L(n) asm volatile("s_waitcnt lgkmcnt(" #n ")" ::: "memory")
; #define PG8_BAR __builtin_amdgcn_s_barrier()
; #define PG8_SCHED __builtin_amdgcn_sched_barrier(0)
; template <class Epi, class Sched, bool ALIGN_EPI = false, bool SP2 = false>
; __device__ __forceinline__ void gemm_phase(PG8_LAS unsigned char* lds, const Gemm g, const Sched& S, const Epi& E, const int tid) {
;     ...
;         for (int t = 0; t < nt; t += 2) {
;     ...
;             PG8_LDA(At, 1, 1); PG8_STAGE(PG8_SB(1, 0), b3, voffB); PG8_STAGE(PG8_SB(1, 1), b3 + hstep, voffB); PG8_STAGE(PG8_SA(1, 0), a3, voffA);
;             PG8_WAIT_V(8); PG8_WAIT_L(0); PG8_BAR; PG8_MMA(1, 0, At, B0); PG8_MMA(1, 1, At, B1); PG8_BAR; PG8_SCHED;
	s_add_i32 s3, s3, s26
	v_lshl_add_u64 v[162:163], v[162:163], 0, s[46:47]
	s_mov_b32 m0, s3
	ds_read_b128 v[176:179], v228 offset:49152
	ds_read_b128 v[180:183], v228 offset:50176
	ds_read_b128 v[186:189], v228 offset:51200
	ds_read_b128 v[190:193], v228 offset:52224
	ds_read_b128 v[194:197], v228 offset:53248
	ds_read_b128 v[198:201], v228 offset:54272
	ds_read_b128 v[202:205], v228 offset:55296
	ds_read_b128 v[206:209], v228 offset:56320
	global_load_lds_dwordx4 v[162:163], off
	s_add_i32 m0, s3, 0x2000
	s_add_u32 s16, s20, 0x160080
	v_lshl_add_u64 v[162:163], v[210:211], 0, s[46:47]
	s_addc_u32 s17, s21, 0
	s_add_i32 s3, s42, s26
	global_load_lds_dwordx4 v[162:163], off
	v_lshl_add_u64 v[162:163], s[16:17], 0, v[2:3]
	s_mov_b32 m0, s3
	s_nop 0
	global_load_lds_dwordx4 v[162:163], off
	v_lshl_add_u64 v[162:163], s[16:17], 0, v[166:167]
	s_add_i32 m0, s3, 0x2000
	s_nop 0
	global_load_lds_dwordx4 v[162:163], off
	v_lshl_add_u64 v[162:163], v[212:213], 0, s[46:47]
	s_mov_b32 m0, s31
	s_nop 0
	global_load_lds_dwordx4 v[162:163], off
	v_lshl_add_u64 v[162:163], v[214:215], 0, s[46:47]
	s_mov_b32 m0, s37
	s_nop 0
	global_load_lds_dwordx4 v[162:163], off
	s_waitcnt vmcnt(8)
	s_waitcnt lgkmcnt(0)
	s_setprio 1
	s_barrier
	v_mfma_f32_16x16x32_bf16 v[64:67], v[134:137], v[176:179], v[64:67]
	v_mfma_f32_16x16x32_bf16 v[60:63], v[142:145], v[176:179], v[60:63]
	v_mfma_f32_16x16x32_bf16 v[48:51], v[134:137], v[186:189], v[48:51]
	v_mfma_f32_16x16x32_bf16 v[44:47], v[142:145], v[186:189], v[44:47]
	v_mfma_f32_16x16x32_bf16 v[32:35], v[134:137], v[194:197], v[32:35]
	v_mfma_f32_16x16x32_bf16 v[28:31], v[142:145], v[194:197], v[28:31]
	v_mfma_f32_16x16x32_bf16 v[16:19], v[134:137], v[202:205], v[16:19]
	v_mfma_f32_16x16x32_bf16 v[12:15], v[142:145], v[202:205], v[12:15]
	v_mfma_f32_16x16x32_bf16 v[64:67], v[138:141], v[180:183], v[64:67]
	v_mfma_f32_16x16x32_bf16 v[60:63], v[146:149], v[180:183], v[60:63]
	v_mfma_f32_16x16x32_bf16 v[48:51], v[138:141], v[190:193], v[48:51]
	v_mfma_f32_16x16x32_bf16 v[44:47], v[146:149], v[190:193], v[44:47]
	v_mfma_f32_16x16x32_bf16 v[32:35], v[138:141], v[198:201], v[32:35]
	v_mfma_f32_16x16x32_bf16 v[28:31], v[146:149], v[198:201], v[28:31]
	v_mfma_f32_16x16x32_bf16 v[16:19], v[138:141], v[206:209], v[16:19]
	v_mfma_f32_16x16x32_bf16 v[12:15], v[146:149], v[206:209], v[12:15]
	v_mfma_f32_16x16x32_bf16 v[56:59], v[150:153], v[176:179], v[56:59]
	v_mfma_f32_16x16x32_bf16 v[52:55], v[158:161], v[176:179], v[52:55]
	v_mfma_f32_16x16x32_bf16 v[40:43], v[150:153], v[186:189], v[40:43]
	v_mfma_f32_16x16x32_bf16 v[36:39], v[158:161], v[186:189], v[36:39]
	v_mfma_f32_16x16x32_bf16 v[24:27], v[150:153], v[194:197], v[24:27]
	v_mfma_f32_16x16x32_bf16 v[20:23], v[158:161], v[194:197], v[20:23]
	v_mfma_f32_16x16x32_bf16 v[8:11], v[150:153], v[202:205], v[8:11]
	v_mfma_f32_16x16x32_bf16 v[4:7], v[158:161], v[202:205], v[4:7]
	v_mfma_f32_16x16x32_bf16 v[56:59], v[154:157], v[180:183], v[56:59]
	v_mfma_f32_16x16x32_bf16 v[52:55], v[172:175], v[180:183], v[52:55]
	v_mfma_f32_16x16x32_bf16 v[40:43], v[154:157], v[190:193], v[40:43]
	v_mfma_f32_16x16x32_bf16 v[36:39], v[172:175], v[190:193], v[36:39]
	v_mfma_f32_16x16x32_bf16 v[24:27], v[154:157], v[198:201], v[24:27]
	v_mfma_f32_16x16x32_bf16 v[20:23], v[172:175], v[198:201], v[20:23]
	v_mfma_f32_16x16x32_bf16 v[8:11], v[154:157], v[206:209], v[8:11]
	v_mfma_f32_16x16x32_bf16 v[4:7], v[172:175], v[206:209], v[4:7]
	s_setprio 0
	s_barrier
	s_add_i32 s75, s75, 2
	s_add_u32 s55, s55, 0x100
	s_addc_u32 s74, s74, 0
	s_cmpk_gt_u32 s75, 0x55
	s_mov_b64 s[16:17], s[18:19]
	s_cbranch_scc1 .LBB0_45

; #define PG8_STAGE(bufoff, gbase, voff) do { _Pragma("unroll") for (int _i = 0; _i < 2; ++_i) \
;         __builtin_amdgcn_global_load_lds((const unsigned*)((const char*)(gbase) + (voff)[_i]), (PG8_LAS unsigned*)(lds + (bufoff) + ldsw + _i * 8192), 16, 0, 0); } while (0)
; #define PG8_LDA(dst, b, h) do { _Pragma("unroll") for (int m = 0; m < 4; ++m) _Pragma("unroll") for (int k = 0; k < 2; ++k) dst[m][k] = *(const PG8_LAS bf16x8*)(lds + PG8_SA(b, h) + aoff + m * 2048 + k * 1024); } while (0)
; #define PG8_LDB(dst, b, h) do { _Pragma("unroll") for (int n = 0; n < 2; ++n) _Pragma("unroll") for (int k = 0; k < 2; ++k) dst[n][k] = *(const PG8_LAS bf16x8*)(lds + PG8_SB(b, h) + boff + n * 2048 + k * 1024); } while (0)
; #define PG8_MMA(ai, bj, At, Bt) do { __builtin_amdgcn_s_setprio(1); _Pragma("unroll") for (int m = 0; m < 4; ++m) _Pragma("unroll") for (int n = 0; n < 2; ++n) _Pragma("unroll") for (int k = 0; k < 2; ++k) \
;         acc[ai][bj][m][n] = __builtin_amdgcn_mfma_f32_16x16x32_bf16(Bt[n][k], At[m][k], acc[ai][bj][m][n], 0, 0, 0); __builtin_amdgcn_s_setprio(0); } while (0)
; #define PG8_WAIT_V(n) asm volatile("s_waitcnt vmcnt(" #n ")" ::: "memory")
; #define PG8_WAIT_L(n) asm volatile("s_waitcnt lgkmcnt(" #n ")" ::: "memory")
; #define PG8_BAR __builtin_amdgcn_s_barrier()
; #define PG8_SCHED __builtin_amdgcn_sched_barrier(0)
; template <class Epi, class Sched, bool ALIGN_EPI = false, bool SP2 = false>
; __device__ __forceinline__ void gemm_phase(PG8_LAS unsigned char* lds, const Gemm g, const Sched& S, const Epi& E, const int tid) {
;     ...
;             const char* a1 = cA + (size_t)(t + 1) * kstep;
;             const char* a2 = last ? nA : cA + (size_t)(t + 2) * kstep; const char* b2 = last ? nB : cB + (size_t)(t + 2) * kstep;
;             const char* a3 = a2 + kstep; const char* b3 = b2 + kstep;
;             if (last && has_next) S.a_ready(nxt);
;             if (last) E.prefetch(lds + EPI_LDS_OFF + wid * 1024, cur, wr, wc, lane);
;             if constexpr (SP2) {
;             PG8_LDB(B0, 0, 0); PG8_LDB(B1, 0, 1); PG8_SCHED; PG8_LDA(At, 0, 0); PG8_STAGE(PG8_SA(1, 1), a1 + hstep, voffA);
;             PG8_WAIT_V(8); PG8_WAIT_L(0); PG8_BAR; PG8_MMA(0, 0, At, B0); PG8_MMA(0, 1, At, B1); PG8_BAR; PG8_SCHED;
;             PG8_LDA(At, 0, 1); PG8_STAGE(PG8_SB(0, 0), b2, voffB); PG8_STAGE(PG8_SB(0, 1), b2 + hstep, voffB); PG8_STAGE(PG8_SA(0, 0), a2, voffA);
.LBB0_74:
	s_add_u32 s30, s24, 0xfff80080
	s_addc_u32 s31, s25, -1
	s_and_b64 s[28:29], s[28:29], exec
	s_cselect_b32 s31, s17, s31
	s_cselect_b32 s30, s23, s30
	s_cselect_b32 s29, s99, s50
	s_cselect_b32 s28, vcc_lo, vcc_hi
	s_add_i32 s42, 0, 0x10000
	v_add_u32_e32 v110, s42, v247
	s_add_i32 s3, 0, 0x14000
	ds_read_b128 v[98:101], v110
	ds_read_b128 v[102:105], v110 offset:1024
	ds_read_b128 v[106:109], v110 offset:2048
	ds_read_b128 v[144:147], v110 offset:3072
	v_add_u32_e32 v110, s3, v247
	ds_read_b128 v[152:155], v110
	ds_read_b128 v[156:159], v110 offset:1024
	ds_read_b128 v[160:163], v110 offset:2048
	ds_read_b128 v[164:167], v110 offset:3072
	v_lshl_add_u64 v[110:111], s[24:25], 0, v[190:191]
	s_add_i32 m0, s49, 0xc000
	ds_read_b128 v[168:171], v253
	ds_read_b128 v[172:175], v253 offset:1024
	ds_read_b128 v[176:179], v253 offset:2048
	ds_read_b128 v[194:197], v253 offset:3072
	ds_read_b128 v[198:201], v253 offset:4096
	ds_read_b128 v[202:205], v253 offset:5120
	ds_read_b128 v[206:209], v253 offset:6144
	ds_read_b128 v[210:213], v253 offset:7168
	global_load_lds_dwordx4 v[110:111], off
	v_lshl_add_u64 v[110:111], s[24:25], 0, v[192:193]
	s_add_i32 m0, s49, 0xe000
	s_nop 0
	global_load_lds_dwordx4 v[110:111], off
	s_waitcnt vmcnt(8)
	s_waitcnt lgkmcnt(0)
	s_setprio 1
	s_barrier
	v_mfma_f32_16x16x32_bf16 v[148:151], v[98:101], v[168:171], v[148:151]
	v_mfma_f32_16x16x32_bf16 v[140:143], v[106:109], v[168:171], v[140:143]
	v_mfma_f32_16x16x32_bf16 v[128:131], v[98:101], v[176:179], v[128:131]
	v_mfma_f32_16x16x32_bf16 v[124:127], v[106:109], v[176:179], v[124:127]
	v_mfma_f32_16x16x32_bf16 v[110:113], v[98:101], v[198:201], v[112:115]
	v_mfma_f32_16x16x32_bf16 v[92:95], v[106:109], v[198:201], v[92:95]
	v_mfma_f32_16x16x32_bf16 v[80:83], v[98:101], v[206:209], v[80:83]
	v_mfma_f32_16x16x32_bf16 v[76:79], v[106:109], v[206:209], v[76:79]
	v_mfma_f32_16x16x32_bf16 v[148:151], v[102:105], v[172:175], v[148:151]
	v_mfma_f32_16x16x32_bf16 v[140:143], v[144:147], v[172:175], v[140:143]
	v_mfma_f32_16x16x32_bf16 v[128:131], v[102:105], v[194:197], v[128:131]
	v_mfma_f32_16x16x32_bf16 v[124:127], v[144:147], v[194:197], v[124:127]
	v_mfma_f32_16x16x32_bf16 v[110:113], v[102:105], v[202:205], v[110:113]
	v_mfma_f32_16x16x32_bf16 v[92:95], v[144:147], v[202:205], v[92:95]
	v_mfma_f32_16x16x32_bf16 v[80:83], v[102:105], v[210:213], v[80:83]
	v_mfma_f32_16x16x32_bf16 v[76:79], v[144:147], v[210:213], v[76:79]
	v_mfma_f32_16x16x32_bf16 v[136:139], v[152:155], v[168:171], v[136:139]
	v_mfma_f32_16x16x32_bf16 v[132:135], v[160:163], v[168:171], v[132:135]
	v_mfma_f32_16x16x32_bf16 v[120:123], v[152:155], v[176:179], v[120:123]
	v_mfma_f32_16x16x32_bf16 v[114:117], v[160:163], v[176:179], v[116:119]
	v_mfma_f32_16x16x32_bf16 v[88:91], v[152:155], v[198:201], v[88:91]
	v_mfma_f32_16x16x32_bf16 v[84:87], v[160:163], v[198:201], v[84:87]
	v_mfma_f32_16x16x32_bf16 v[72:75], v[152:155], v[206:209], v[72:75]
	v_mfma_f32_16x16x32_bf16 v[68:71], v[160:163], v[206:209], v[68:71]
	v_mfma_f32_16x16x32_bf16 v[136:139], v[156:159], v[172:175], v[136:139]
	v_mfma_f32_16x16x32_bf16 v[132:135], v[164:167], v[172:175], v[132:135]
	v_mfma_f32_16x16x32_bf16 v[120:123], v[156:159], v[194:197], v[120:123]
	v_mfma_f32_16x16x32_bf16 v[116:119], v[164:167], v[194:197], v[114:117]
	v_mfma_f32_16x16x32_bf16 v[88:91], v[156:159], v[202:205], v[88:91]
	v_mfma_f32_16x16x32_bf16 v[84:87], v[164:167], v[202:205], v[84:87]
	v_mfma_f32_16x16x32_bf16 v[72:75], v[156:159], v[210:213], v[72:75]
	v_mfma_f32_16x16x32_bf16 v[68:71], v[164:167], v[210:213], v[68:71]
	s_setprio 0
	s_barrier
	s_add_i32 s42, s42, s48
	v_lshl_add_u64 v[180:181], s[28:29], 0, v[2:3]
	s_mov_b32 m0, s42
	ds_read_b128 v[168:171], v253 offset:16384
	ds_read_b128 v[172:175], v253 offset:17408
	ds_read_b128 v[176:179], v253 offset:18432
	ds_read_b128 v[194:197], v253 offset:19456
	ds_read_b128 v[198:201], v253 offset:20480
	ds_read_b128 v[202:205], v253 offset:21504
	ds_read_b128 v[206:209], v253 offset:22528
	ds_read_b128 v[210:213], v253 offset:23552
	global_load_lds_dwordx4 v[180:181], off
	s_add_i32 m0, s42, 0x2000
	s_add_u32 s42, s28, 0x80000
	v_lshl_add_u64 v[182:183], s[28:29], 0, v[188:189]
	s_addc_u32 s43, s29, 0
	s_add_i32 s3, s3, s48
	global_load_lds_dwordx4 v[182:183], off
	v_lshl_add_u64 v[114:115], s[42:43], 0, v[2:3]
	s_mov_b32 m0, s3
	v_lshl_add_u64 v[214:215], s[30:31], 0, v[0:1]
	global_load_lds_dwordx4 v[114:115], off
	v_lshl_add_u64 v[114:115], s[42:43], 0, v[188:189]
	s_add_i32 m0, s3, 0x2000
	v_lshl_add_u64 v[216:217], s[30:31], 0, v[186:187]
	global_load_lds_dwordx4 v[114:115], off
	s_mov_b32 m0, s49
	s_nop 0
	global_load_lds_dwordx4 v[214:215], off
	s_mov_b32 m0, s52
	s_nop 0
	global_load_lds_dwordx4 v[216:217], off
	s_waitcnt vmcnt(8)
	s_waitcnt lgkmcnt(0)
	s_setprio 1
	s_barrier
; #define PG8_STAGE(bufoff, gbase, voff) do { _Pragma("unroll") for (int _i = 0; _i < 2; ++_i) \
;         __builtin_amdgcn_global_load_lds((const unsigned*)((const char*)(gbase) + (voff)[_i]), (PG8_LAS unsigned*)(lds + (bufoff) + ldsw + _i * 8192), 16, 0, 0); } while (0)
; #define PG8_LDA(dst, b, h) do { _Pragma("unroll") for (int m = 0; m < 4; ++m) _Pragma("unroll") for (int k = 0; k < 2; ++k) dst[m][k] = *(const PG8_LAS bf16x8*)(lds + PG8_SA(b, h) + aoff + m * 2048 + k * 1024); } while (0)
; #define PG8_LDB(dst, b, h) do { _Pragma("unroll") for (int n = 0; n < 2; ++n) _Pragma("unroll") for (int k = 0; k < 2; ++k) dst[n][k] = *(const PG8_LAS bf16x8*)(lds + PG8_SB(b, h) + boff + n * 2048 + k * 1024); } while (0)
; #define PG8_MMA(ai, bj, At, Bt) do { __builtin_amdgcn_s_setprio(1); _Pragma("unroll") for (int m = 0; m < 4; ++m) _Pragma("unroll") for (int n = 0; n < 2; ++n) _Pragma("unroll") for (int k = 0; k < 2; ++k) \
;         acc[ai][bj][m][n] = __builtin_amdgcn_mfma_f32_16x16x32_bf16(Bt[n][k], At[m][k], acc[ai][bj][m][n], 0, 0, 0); __builtin_amdgcn_s_setprio(0); } while (0)
; #define PG8_WAIT_V(n) asm volatile("s_waitcnt vmcnt(" #n ")" ::: "memory")
; #define PG8_WAIT_L(n) asm volatile("s_waitcnt lgkmcnt(" #n ")" ::: "memory")
; #define PG8_BAR __builtin_amdgcn_s_barrier()
; #define PG8_SCHED __builtin_amdgcn_sched_barrier(0)
; template <class Epi, class Sched, bool ALIGN_EPI = false, bool SP2 = false>
; __device__ __forceinline__ void gemm_phase(PG8_LAS unsigned char* lds, const Gemm g, const Sched& S, const Epi& E, const int tid) {
;     ...
;             PG8_WAIT_V(8); PG8_WAIT_L(0); PG8_BAR; PG8_MMA(1, 0, At, B0); PG8_MMA(1, 1, At, B1); PG8_BAR; PG8_SCHED;
;             PG8_LDB(B0, 1, 0); PG8_LDB(B1, 1, 1); PG8_SCHED; PG8_LDA(At, 1, 0); PG8_STAGE(PG8_SA(0, 1), a2 + hstep, voffA);
;             PG8_WAIT_V(8); PG8_WAIT_L(0); PG8_BAR; PG8_MMA(0, 0, At, B0); PG8_MMA(0, 1, At, B1); PG8_BAR; PG8_SCHED;
	v_mfma_f32_16x16x32_bf16 v[64:67], v[98:101], v[168:171], v[64:67]
	v_mfma_f32_16x16x32_bf16 v[60:63], v[106:109], v[168:171], v[60:63]
	v_mfma_f32_16x16x32_bf16 v[48:51], v[98:101], v[176:179], v[48:51]
	v_mfma_f32_16x16x32_bf16 v[44:47], v[106:109], v[176:179], v[44:47]
	v_mfma_f32_16x16x32_bf16 v[32:35], v[98:101], v[198:201], v[32:35]
	v_mfma_f32_16x16x32_bf16 v[28:31], v[106:109], v[198:201], v[28:31]
	v_mfma_f32_16x16x32_bf16 v[16:19], v[98:101], v[206:209], v[16:19]
	v_mfma_f32_16x16x32_bf16 v[12:15], v[106:109], v[206:209], v[12:15]
	v_mfma_f32_16x16x32_bf16 v[64:67], v[102:105], v[172:175], v[64:67]
	v_mfma_f32_16x16x32_bf16 v[60:63], v[144:147], v[172:175], v[60:63]
	v_mfma_f32_16x16x32_bf16 v[48:51], v[102:105], v[194:197], v[48:51]
	v_mfma_f32_16x16x32_bf16 v[44:47], v[144:147], v[194:197], v[44:47]
	v_mfma_f32_16x16x32_bf16 v[32:35], v[102:105], v[202:205], v[32:35]
	v_mfma_f32_16x16x32_bf16 v[28:31], v[144:147], v[202:205], v[28:31]
	v_mfma_f32_16x16x32_bf16 v[16:19], v[102:105], v[210:213], v[16:19]
	v_mfma_f32_16x16x32_bf16 v[12:15], v[144:147], v[210:213], v[12:15]
	v_mfma_f32_16x16x32_bf16 v[56:59], v[152:155], v[168:171], v[56:59]
	v_mfma_f32_16x16x32_bf16 v[52:55], v[160:163], v[168:171], v[52:55]
	v_mfma_f32_16x16x32_bf16 v[40:43], v[152:155], v[176:179], v[40:43]
	v_mfma_f32_16x16x32_bf16 v[36:39], v[160:163], v[176:179], v[36:39]
	v_mfma_f32_16x16x32_bf16 v[24:27], v[152:155], v[198:201], v[24:27]
	v_mfma_f32_16x16x32_bf16 v[20:23], v[160:163], v[198:201], v[20:23]
	v_mfma_f32_16x16x32_bf16 v[8:11], v[152:155], v[206:209], v[8:11]
	v_mfma_f32_16x16x32_bf16 v[4:7], v[160:163], v[206:209], v[4:7]
	v_mfma_f32_16x16x32_bf16 v[56:59], v[156:159], v[172:175], v[56:59]
	v_mfma_f32_16x16x32_bf16 v[52:55], v[164:167], v[172:175], v[52:55]
	v_mfma_f32_16x16x32_bf16 v[40:43], v[156:159], v[194:197], v[40:43]
	v_mfma_f32_16x16x32_bf16 v[36:39], v[164:167], v[194:197], v[36:39]
	v_mfma_f32_16x16x32_bf16 v[24:27], v[156:159], v[202:205], v[24:27]
	v_mfma_f32_16x16x32_bf16 v[20:23], v[164:167], v[202:205], v[20:23]
	v_mfma_f32_16x16x32_bf16 v[8:11], v[156:159], v[210:213], v[8:11]
	v_mfma_f32_16x16x32_bf16 v[4:7], v[164:167], v[210:213], v[4:7]
	s_setprio 0
	s_barrier
	s_add_i32 s3, 0, 0x18000
	v_add_u32_e32 v114, s3, v247
	s_add_i32 s42, 0, 0x1c000
	ds_read_b128 v[98:101], v114
	ds_read_b128 v[102:105], v114 offset:1024
	ds_read_b128 v[106:109], v114 offset:2048
	ds_read_b128 v[144:147], v114 offset:3072
	v_add_u32_e32 v114, s42, v247
	ds_read_b128 v[152:155], v114
	ds_read_b128 v[156:159], v114 offset:1024
	ds_read_b128 v[160:163], v114 offset:2048
	ds_read_b128 v[164:167], v114 offset:3072
	s_add_u32 s30, s30, 0x80000
	s_addc_u32 s31, s31, 0
	s_mov_b32 m0, s53
	v_lshl_add_u64 v[114:115], s[30:31], 0, v[0:1]
	ds_read_b128 v[168:171], v253 offset:32768
	ds_read_b128 v[172:175], v253 offset:33792
	ds_read_b128 v[176:179], v253 offset:34816
	ds_read_b128 v[194:197], v253 offset:35840
	ds_read_b128 v[198:201], v253 offset:36864
	ds_read_b128 v[202:205], v253 offset:37888
	ds_read_b128 v[206:209], v253 offset:38912
	ds_read_b128 v[210:213], v253 offset:39936
	global_load_lds_dwordx4 v[114:115], off
	v_lshl_add_u64 v[114:115], s[30:31], 0, v[186:187]
	s_mov_b32 m0, s54
	s_nop 0
	global_load_lds_dwordx4 v[114:115], off
	s_waitcnt vmcnt(8)
	s_waitcnt lgkmcnt(0)
	s_setprio 1
	s_barrier
	v_mfma_f32_16x16x32_bf16 v[148:151], v[98:101], v[168:171], v[148:151]
	v_mfma_f32_16x16x32_bf16 v[140:143], v[106:109], v[168:171], v[140:143]
	v_mfma_f32_16x16x32_bf16 v[128:131], v[98:101], v[176:179], v[128:131]
	v_mfma_f32_16x16x32_bf16 v[124:127], v[106:109], v[176:179], v[124:127]
	v_mfma_f32_16x16x32_bf16 v[110:113], v[98:101], v[198:201], v[110:113]
	v_mfma_f32_16x16x32_bf16 v[92:95], v[106:109], v[198:201], v[92:95]
	v_mfma_f32_16x16x32_bf16 v[80:83], v[98:101], v[206:209], v[80:83]
	v_mfma_f32_16x16x32_bf16 v[76:79], v[106:109], v[206:209], v[76:79]
	v_mfma_f32_16x16x32_bf16 v[148:151], v[102:105], v[172:175], v[148:151]
	v_mfma_f32_16x16x32_bf16 v[140:143], v[144:147], v[172:175], v[140:143]
	v_mfma_f32_16x16x32_bf16 v[128:131], v[102:105], v[194:197], v[128:131]
	v_mfma_f32_16x16x32_bf16 v[124:127], v[144:147], v[194:197], v[124:127]
	v_mfma_f32_16x16x32_bf16 v[112:115], v[102:105], v[202:205], v[110:113]
	v_mfma_f32_16x16x32_bf16 v[92:95], v[144:147], v[202:205], v[92:95]
	v_mfma_f32_16x16x32_bf16 v[80:83], v[102:105], v[210:213], v[80:83]
	v_mfma_f32_16x16x32_bf16 v[76:79], v[144:147], v[210:213], v[76:79]
	v_mfma_f32_16x16x32_bf16 v[136:139], v[152:155], v[168:171], v[136:139]
	v_mfma_f32_16x16x32_bf16 v[132:135], v[160:163], v[168:171], v[132:135]
	v_mfma_f32_16x16x32_bf16 v[120:123], v[152:155], v[176:179], v[120:123]
	v_mfma_f32_16x16x32_bf16 v[116:119], v[160:163], v[176:179], v[116:119]
	v_mfma_f32_16x16x32_bf16 v[88:91], v[152:155], v[198:201], v[88:91]
	v_mfma_f32_16x16x32_bf16 v[84:87], v[160:163], v[198:201], v[84:87]
	v_mfma_f32_16x16x32_bf16 v[72:75], v[152:155], v[206:209], v[72:75]
	v_mfma_f32_16x16x32_bf16 v[68:71], v[160:163], v[206:209], v[68:71]
	v_mfma_f32_16x16x32_bf16 v[136:139], v[156:159], v[172:175], v[136:139]
	v_mfma_f32_16x16x32_bf16 v[132:135], v[164:167], v[172:175], v[132:135]
	v_mfma_f32_16x16x32_bf16 v[120:123], v[156:159], v[194:197], v[120:123]
	v_mfma_f32_16x16x32_bf16 v[116:119], v[164:167], v[194:197], v[116:119]
	v_mfma_f32_16x16x32_bf16 v[88:91], v[156:159], v[202:205], v[88:91]
	v_mfma_f32_16x16x32_bf16 v[84:87], v[164:167], v[202:205], v[84:87]
	v_mfma_f32_16x16x32_bf16 v[72:75], v[156:159], v[210:213], v[72:75]
	v_mfma_f32_16x16x32_bf16 v[68:71], v[164:167], v[210:213], v[68:71]
	s_setprio 0
	s_barrier
; #define PG8_STAGE(bufoff, gbase, voff) do { _Pragma("unroll") for (int _i = 0; _i < 2; ++_i) \
;         __builtin_amdgcn_global_load_lds((const unsigned*)((const char*)(gbase) + (voff)[_i]), (PG8_LAS unsigned*)(lds + (bufoff) + ldsw + _i * 8192), 16, 0, 0); } while (0)
; #define PG8_LDA(dst, b, h) do { _Pragma("unroll") for (int m = 0; m < 4; ++m) _Pragma("unroll") for (int k = 0; k < 2; ++k) dst[m][k] = *(const PG8_LAS bf16x8*)(lds + PG8_SA(b, h) + aoff + m * 2048 + k * 1024); } while (0)
; #define PG8_MMA(ai, bj, At, Bt) do { __builtin_amdgcn_s_setprio(1); _Pragma("unroll") for (int m = 0; m < 4; ++m) _Pragma("unroll") for (int n = 0; n < 2; ++n) _Pragma("unroll") for (int k = 0; k < 2; ++k) \
;         acc[ai][bj][m][n] = __builtin_amdgcn_mfma_f32_16x16x32_bf16(Bt[n][k], At[m][k], acc[ai][bj][m][n], 0, 0, 0); __builtin_amdgcn_s_setprio(0); } while (0)
; #define PG8_WAIT_V(n) asm volatile("s_waitcnt vmcnt(" #n ")" ::: "memory")
; #define PG8_WAIT_L(n) asm volatile("s_waitcnt lgkmcnt(" #n ")" ::: "memory")
; #define PG8_BAR __builtin_amdgcn_s_barrier()
; #define PG8_SCHED __builtin_amdgcn_sched_barrier(0)
; template <class Epi, class Sched, bool ALIGN_EPI = false, bool SP2 = false>
; __device__ __forceinline__ void gemm_phase(PG8_LAS unsigned char* lds, const Gemm g, const Sched& S, const Epi& E, const int tid) {
;     ...
;             PG8_LDA(At, 1, 1); PG8_STAGE(PG8_SB(1, 0), b3, voffB); PG8_STAGE(PG8_SB(1, 1), b3 + hstep, voffB); PG8_STAGE(PG8_SA(1, 0), a3, voffA);
;             PG8_WAIT_V(8); PG8_WAIT_L(0); PG8_BAR; PG8_MMA(1, 0, At, B0); PG8_MMA(1, 1, At, B1); PG8_BAR; PG8_SCHED;
	s_add_i32 s3, s3, s48
	v_lshl_add_u64 v[110:111], v[180:181], 0, s[46:47]
	s_mov_b32 m0, s3
	ds_read_b128 v[168:171], v253 offset:49152
	ds_read_b128 v[172:175], v253 offset:50176
	ds_read_b128 v[176:179], v253 offset:51200
	ds_read_b128 v[194:197], v253 offset:52224
	ds_read_b128 v[198:201], v253 offset:53248
	ds_read_b128 v[202:205], v253 offset:54272
	ds_read_b128 v[206:209], v253 offset:55296
	ds_read_b128 v[210:213], v253 offset:56320
	global_load_lds_dwordx4 v[110:111], off
	s_add_i32 m0, s3, 0x2000
	s_add_u32 s28, s28, 0x80080
	v_lshl_add_u64 v[110:111], v[182:183], 0, s[46:47]
	s_addc_u32 s29, s29, 0
	s_add_i32 s3, s42, s48
	global_load_lds_dwordx4 v[110:111], off
	v_lshl_add_u64 v[110:111], s[28:29], 0, v[2:3]
	s_mov_b32 m0, s3
	s_nop 0
	global_load_lds_dwordx4 v[110:111], off
	v_lshl_add_u64 v[110:111], s[28:29], 0, v[188:189]
	s_add_i32 m0, s3, 0x2000
	s_nop 0
	global_load_lds_dwordx4 v[110:111], off
	v_lshl_add_u64 v[110:111], v[214:215], 0, s[46:47]
	s_mov_b32 m0, s55
	s_nop 0
	global_load_lds_dwordx4 v[110:111], off
	v_lshl_add_u64 v[110:111], v[216:217], 0, s[46:47]
	s_mov_b32 m0, s74
	s_nop 0
	global_load_lds_dwordx4 v[110:111], off
	s_waitcnt vmcnt(8)
	s_waitcnt lgkmcnt(0)
	s_setprio 1
	s_barrier
	v_mfma_f32_16x16x32_bf16 v[64:67], v[98:101], v[168:171], v[64:67]
	v_mfma_f32_16x16x32_bf16 v[60:63], v[106:109], v[168:171], v[60:63]
	v_mfma_f32_16x16x32_bf16 v[48:51], v[98:101], v[176:179], v[48:51]
	v_mfma_f32_16x16x32_bf16 v[44:47], v[106:109], v[176:179], v[44:47]
	v_mfma_f32_16x16x32_bf16 v[32:35], v[98:101], v[198:201], v[32:35]
	v_mfma_f32_16x16x32_bf16 v[28:31], v[106:109], v[198:201], v[28:31]
	v_mfma_f32_16x16x32_bf16 v[16:19], v[98:101], v[206:209], v[16:19]
	v_mfma_f32_16x16x32_bf16 v[12:15], v[106:109], v[206:209], v[12:15]
	v_mfma_f32_16x16x32_bf16 v[64:67], v[102:105], v[172:175], v[64:67]
	v_mfma_f32_16x16x32_bf16 v[60:63], v[144:147], v[172:175], v[60:63]
	v_mfma_f32_16x16x32_bf16 v[48:51], v[102:105], v[194:197], v[48:51]
	v_mfma_f32_16x16x32_bf16 v[44:47], v[144:147], v[194:197], v[44:47]
	v_mfma_f32_16x16x32_bf16 v[32:35], v[102:105], v[202:205], v[32:35]
	v_mfma_f32_16x16x32_bf16 v[28:31], v[144:147], v[202:205], v[28:31]
	v_mfma_f32_16x16x32_bf16 v[16:19], v[102:105], v[210:213], v[16:19]
	v_mfma_f32_16x16x32_bf16 v[12:15], v[144:147], v[210:213], v[12:15]
	v_mfma_f32_16x16x32_bf16 v[56:59], v[152:155], v[168:171], v[56:59]
	v_mfma_f32_16x16x32_bf16 v[52:55], v[160:163], v[168:171], v[52:55]
	v_mfma_f32_16x16x32_bf16 v[40:43], v[152:155], v[176:179], v[40:43]
	v_mfma_f32_16x16x32_bf16 v[36:39], v[160:163], v[176:179], v[36:39]
	v_mfma_f32_16x16x32_bf16 v[24:27], v[152:155], v[198:201], v[24:27]
	v_mfma_f32_16x16x32_bf16 v[20:23], v[160:163], v[198:201], v[20:23]
	v_mfma_f32_16x16x32_bf16 v[8:11], v[152:155], v[206:209], v[8:11]
	v_mfma_f32_16x16x32_bf16 v[4:7], v[160:163], v[206:209], v[4:7]
	v_mfma_f32_16x16x32_bf16 v[56:59], v[156:159], v[172:175], v[56:59]
	v_mfma_f32_16x16x32_bf16 v[52:55], v[164:167], v[172:175], v[52:55]
	v_mfma_f32_16x16x32_bf16 v[40:43], v[156:159], v[194:197], v[40:43]
	v_mfma_f32_16x16x32_bf16 v[36:39], v[164:167], v[194:197], v[36:39]
	v_mfma_f32_16x16x32_bf16 v[24:27], v[156:159], v[202:205], v[24:27]
	v_mfma_f32_16x16x32_bf16 v[20:23], v[164:167], v[202:205], v[20:23]
	v_mfma_f32_16x16x32_bf16 v[8:11], v[156:159], v[210:213], v[8:11]
	v_mfma_f32_16x16x32_bf16 v[4:7], v[164:167], v[210:213], v[4:7]
	s_setprio 0
	s_barrier
	s_add_i32 s51, s51, 2
	s_add_u32 s24, s24, 0x100
	s_addc_u32 s25, s25, 0
	s_add_u32 vcc_hi, vcc_hi, 0x100
	s_addc_u32 s50, s50, 0
	s_cmp_gt_u32 s51, 29
	s_cbranch_scc1 .LBB0_77

; #define PG8_STAGE(bufoff, gbase, voff) do { _Pragma("unroll") for (int _i = 0; _i < 2; ++_i) \
;         __builtin_amdgcn_global_load_lds((const unsigned*)((const char*)(gbase) + (voff)[_i]), (PG8_LAS unsigned*)(lds + (bufoff) + ldsw + _i * 8192), 16, 0, 0); } while (0)
; #define PG8_LDA(dst, b, h) do { _Pragma("unroll") for (int m = 0; m < 4; ++m) _Pragma("unroll") for (int k = 0; k < 2; ++k) dst[m][k] = *(const PG8_LAS bf16x8*)(lds + PG8_SA(b, h) + aoff + m * 2048 + k * 1024); } while (0)
; #define PG8_LDB(dst, b, h) do { _Pragma("unroll") for (int n = 0; n < 2; ++n) _Pragma("unroll") for (int k = 0; k < 2; ++k) dst[n][k] = *(const PG8_LAS bf16x8*)(lds + PG8_SB(b, h) + boff + n * 2048 + k * 1024); } while (0)
; #define PG8_MMA(ai, bj, At, Bt) do { __builtin_amdgcn_s_setprio(1); _Pragma("unroll") for (int m = 0; m < 4; ++m) _Pragma("unroll") for (int n = 0; n < 2; ++n) _Pragma("unroll") for (int k = 0; k < 2; ++k) \
;         acc[ai][bj][m][n] = __builtin_amdgcn_mfma_f32_16x16x32_bf16(Bt[n][k], At[m][k], acc[ai][bj][m][n], 0, 0, 0); __builtin_amdgcn_s_setprio(0); } while (0)
; #define PG8_WAIT_V(n) asm volatile("s_waitcnt vmcnt(" #n ")" ::: "memory")
; #define PG8_WAIT_L(n) asm volatile("s_waitcnt lgkmcnt(" #n ")" ::: "memory")
; #define PG8_BAR __builtin_amdgcn_s_barrier()
; #define PG8_SCHED __builtin_amdgcn_sched_barrier(0)
; template <class Epi, class Sched, bool ALIGN_EPI = false, bool SP2 = false>
; __device__ __forceinline__ void gemm_phase(PG8_LAS unsigned char* lds, const Gemm g, const Sched& S, const Epi& E, const int tid) {
;     ...
;             const char* a1 = cA + (size_t)(t + 1) * kstep;
;             const char* a2 = last ? nA : cA + (size_t)(t + 2) * kstep; const char* b2 = last ? nB : cB + (size_t)(t + 2) * kstep;
;             const char* a3 = a2 + kstep; const char* b3 = b2 + kstep;
;             if (last && has_next) S.a_ready(nxt);
;             if (last) E.prefetch(lds + EPI_LDS_OFF + wid * 1024, cur, wr, wc, lane);
;             if constexpr (SP2) {
;             PG8_LDB(B0, 0, 0); PG8_LDB(B1, 0, 1); PG8_SCHED; PG8_LDA(At, 0, 0); PG8_STAGE(PG8_SA(1, 1), a1 + hstep, voffA);
;             PG8_WAIT_V(8); PG8_WAIT_L(0); PG8_BAR; PG8_MMA(0, 0, At, B0); PG8_MMA(0, 1, At, B1); PG8_BAR; PG8_SCHED;
;             PG8_LDA(At, 0, 1); PG8_STAGE(PG8_SB(0, 0), b2, voffB); PG8_STAGE(PG8_SB(0, 1), b2 + hstep, voffB); PG8_STAGE(PG8_SA(0, 0), a2, voffA);
.LBB0_156:
	s_add_u32 s3, s26, 0xfff80080
	s_addc_u32 s30, s27, -1
	s_and_b64 s[28:29], s[28:29], exec
	s_cselect_b32 s31, s9, s30
	s_cselect_b32 s30, s17, s3
	s_cselect_b32 s29, s15, s25
	s_cselect_b32 s28, s39, s23
	s_add_i32 s3, 0, 0x10000
	v_add_u32_e32 v34, s3, v167
	s_add_i32 s51, 0, 0x14000
	ds_read_b128 v[44:47], v34
	ds_read_b128 v[48:51], v34 offset:1024
	ds_read_b128 v[160:163], v34 offset:2048
	ds_read_b128 v[172:175], v34 offset:3072
	v_add_u32_e32 v34, s51, v167
	ds_read_b128 v[176:179], v34
	ds_read_b128 v[180:183], v34 offset:1024
	ds_read_b128 v[186:189], v34 offset:2048
	ds_read_b128 v[190:193], v34 offset:3072
	v_lshl_add_u64 v[34:35], s[26:27], 0, v[156:157]
	s_add_i32 m0, s48, 0xc000
	ds_read_b128 v[194:197], v171
	ds_read_b128 v[198:201], v171 offset:1024
	ds_read_b128 v[202:205], v171 offset:2048
	ds_read_b128 v[206:209], v171 offset:3072
	ds_read_b128 v[210:213], v171 offset:4096
	ds_read_b128 v[214:217], v171 offset:5120
	ds_read_b128 v[218:221], v171 offset:6144
	ds_read_b128 v[222:225], v171 offset:7168
	global_load_lds_dwordx4 v[34:35], off
	v_lshl_add_u64 v[34:35], s[26:27], 0, v[158:159]
	s_add_i32 m0, s48, 0xe000
	s_nop 0
	global_load_lds_dwordx4 v[34:35], off
	s_waitcnt vmcnt(8)
	s_waitcnt lgkmcnt(0)
	s_setprio 1
	s_barrier
	v_mfma_f32_16x16x32_bf16 v[144:147], v[44:47], v[194:197], v[144:147]
	v_mfma_f32_16x16x32_bf16 v[140:143], v[160:163], v[194:197], v[140:143]
	v_mfma_f32_16x16x32_bf16 v[128:131], v[44:47], v[202:205], v[128:131]
	v_mfma_f32_16x16x32_bf16 v[124:127], v[160:163], v[202:205], v[124:127]
	v_mfma_f32_16x16x32_bf16 v[112:115], v[44:47], v[210:213], v[112:115]
	v_mfma_f32_16x16x32_bf16 v[108:111], v[160:163], v[210:213], v[108:111]
	v_mfma_f32_16x16x32_bf16 v[96:99], v[44:47], v[218:221], v[96:99]
	v_mfma_f32_16x16x32_bf16 v[92:95], v[160:163], v[218:221], v[92:95]
	v_mfma_f32_16x16x32_bf16 v[144:147], v[48:51], v[198:201], v[144:147]
	v_mfma_f32_16x16x32_bf16 v[140:143], v[172:175], v[198:201], v[140:143]
	v_mfma_f32_16x16x32_bf16 v[128:131], v[48:51], v[206:209], v[128:131]
	v_mfma_f32_16x16x32_bf16 v[124:127], v[172:175], v[206:209], v[124:127]
	v_mfma_f32_16x16x32_bf16 v[112:115], v[48:51], v[214:217], v[112:115]
	v_mfma_f32_16x16x32_bf16 v[108:111], v[172:175], v[214:217], v[108:111]
	v_mfma_f32_16x16x32_bf16 v[96:99], v[48:51], v[222:225], v[96:99]
	v_mfma_f32_16x16x32_bf16 v[92:95], v[172:175], v[222:225], v[92:95]
	v_mfma_f32_16x16x32_bf16 v[136:139], v[176:179], v[194:197], v[136:139]
	v_mfma_f32_16x16x32_bf16 v[132:135], v[186:189], v[194:197], v[132:135]
	v_mfma_f32_16x16x32_bf16 v[120:123], v[176:179], v[202:205], v[120:123]
	v_mfma_f32_16x16x32_bf16 v[116:119], v[186:189], v[202:205], v[116:119]
	v_mfma_f32_16x16x32_bf16 v[104:107], v[176:179], v[210:213], v[104:107]
	v_mfma_f32_16x16x32_bf16 v[100:103], v[186:189], v[210:213], v[100:103]
	v_mfma_f32_16x16x32_bf16 v[88:91], v[176:179], v[218:221], v[88:91]
	v_mfma_f32_16x16x32_bf16 v[84:87], v[186:189], v[218:221], v[84:87]
	v_mfma_f32_16x16x32_bf16 v[136:139], v[180:183], v[198:201], v[136:139]
	v_mfma_f32_16x16x32_bf16 v[132:135], v[190:193], v[198:201], v[132:135]
	v_mfma_f32_16x16x32_bf16 v[120:123], v[180:183], v[206:209], v[120:123]
	v_mfma_f32_16x16x32_bf16 v[116:119], v[190:193], v[206:209], v[116:119]
	v_mfma_f32_16x16x32_bf16 v[104:107], v[180:183], v[214:217], v[104:107]
	v_mfma_f32_16x16x32_bf16 v[100:103], v[190:193], v[214:217], v[100:103]
	v_mfma_f32_16x16x32_bf16 v[88:91], v[180:183], v[222:225], v[88:91]
	v_mfma_f32_16x16x32_bf16 v[84:87], v[190:193], v[222:225], v[84:87]
	s_setprio 0
	s_barrier
	s_add_i32 s3, s3, s44
	v_lshl_add_u64 v[164:165], s[28:29], 0, v[2:3]
	s_mov_b32 m0, s3
	ds_read_b128 v[194:197], v171 offset:16384
	ds_read_b128 v[198:201], v171 offset:17408
	ds_read_b128 v[202:205], v171 offset:18432
	ds_read_b128 v[206:209], v171 offset:19456
	ds_read_b128 v[210:213], v171 offset:20480
	ds_read_b128 v[214:217], v171 offset:21504
	ds_read_b128 v[218:221], v171 offset:22528
	ds_read_b128 v[222:225], v171 offset:23552
	global_load_lds_dwordx4 v[164:165], off
	s_add_i32 m0, s3, 0x2000
	s_add_u32 s42, s28, 0x80000
	v_lshl_add_u64 v[226:227], s[28:29], 0, v[150:151]
	s_addc_u32 s43, s29, 0
	s_add_i32 s3, s51, s44
	global_load_lds_dwordx4 v[226:227], off
	v_lshl_add_u64 v[34:35], s[42:43], 0, v[2:3]
	s_mov_b32 m0, s3
	v_lshl_add_u64 v[228:229], s[30:31], 0, v[0:1]
	global_load_lds_dwordx4 v[34:35], off
	v_lshl_add_u64 v[34:35], s[42:43], 0, v[150:151]
	s_add_i32 m0, s3, 0x2000
	v_lshl_add_u64 v[230:231], s[30:31], 0, v[148:149]
	global_load_lds_dwordx4 v[34:35], off
	s_mov_b32 m0, s48
	s_nop 0
	global_load_lds_dwordx4 v[228:229], off
	s_mov_b32 m0, s49
	s_nop 0
	global_load_lds_dwordx4 v[230:231], off
	s_waitcnt vmcnt(8)
	s_waitcnt lgkmcnt(0)
	s_setprio 1
	s_barrier
; #define PG8_STAGE(bufoff, gbase, voff) do { _Pragma("unroll") for (int _i = 0; _i < 2; ++_i) \
;         __builtin_amdgcn_global_load_lds((const unsigned*)((const char*)(gbase) + (voff)[_i]), (PG8_LAS unsigned*)(lds + (bufoff) + ldsw + _i * 8192), 16, 0, 0); } while (0)
; #define PG8_LDA(dst, b, h) do { _Pragma("unroll") for (int m = 0; m < 4; ++m) _Pragma("unroll") for (int k = 0; k < 2; ++k) dst[m][k] = *(const PG8_LAS bf16x8*)(lds + PG8_SA(b, h) + aoff + m * 2048 + k * 1024); } while (0)
; #define PG8_LDB(dst, b, h) do { _Pragma("unroll") for (int n = 0; n < 2; ++n) _Pragma("unroll") for (int k = 0; k < 2; ++k) dst[n][k] = *(const PG8_LAS bf16x8*)(lds + PG8_SB(b, h) + boff + n * 2048 + k * 1024); } while (0)
; #define PG8_MMA(ai, bj, At, Bt) do { __builtin_amdgcn_s_setprio(1); _Pragma("unroll") for (int m = 0; m < 4; ++m) _Pragma("unroll") for (int n = 0; n < 2; ++n) _Pragma("unroll") for (int k = 0; k < 2; ++k) \
;         acc[ai][bj][m][n] = __builtin_amdgcn_mfma_f32_16x16x32_bf16(Bt[n][k], At[m][k], acc[ai][bj][m][n], 0, 0, 0); __builtin_amdgcn_s_setprio(0); } while (0)
; #define PG8_WAIT_V(n) asm volatile("s_waitcnt vmcnt(" #n ")" ::: "memory")
; #define PG8_WAIT_L(n) asm volatile("s_waitcnt lgkmcnt(" #n ")" ::: "memory")
; #define PG8_BAR __builtin_amdgcn_s_barrier()
; #define PG8_SCHED __builtin_amdgcn_sched_barrier(0)
; template <class Epi, class Sched, bool ALIGN_EPI = false, bool SP2 = false>
; __device__ __forceinline__ void gemm_phase(PG8_LAS unsigned char* lds, const Gemm g, const Sched& S, const Epi& E, const int tid) {
;     ...
;             PG8_WAIT_V(8); PG8_WAIT_L(0); PG8_BAR; PG8_MMA(1, 0, At, B0); PG8_MMA(1, 1, At, B1); PG8_BAR; PG8_SCHED;
;             PG8_LDB(B0, 1, 0); PG8_LDB(B1, 1, 1); PG8_SCHED; PG8_LDA(At, 1, 0); PG8_STAGE(PG8_SA(0, 1), a2 + hstep, voffA);
;             PG8_WAIT_V(8); PG8_WAIT_L(0); PG8_BAR; PG8_MMA(0, 0, At, B0); PG8_MMA(0, 1, At, B1); PG8_BAR; PG8_SCHED;
	v_mfma_f32_16x16x32_bf16 v[80:83], v[44:47], v[194:197], v[80:83]
	v_mfma_f32_16x16x32_bf16 v[76:79], v[160:163], v[194:197], v[76:79]
	v_mfma_f32_16x16x32_bf16 v[64:67], v[44:47], v[202:205], v[64:67]
	v_mfma_f32_16x16x32_bf16 v[60:63], v[160:163], v[202:205], v[60:63]
	v_mfma_f32_16x16x32_bf16 v[40:43], v[44:47], v[210:213], v[40:43]
	v_mfma_f32_16x16x32_bf16 v[34:37], v[160:163], v[210:213], v[36:39]
	v_mfma_f32_16x16x32_bf16 v[16:19], v[44:47], v[218:221], v[16:19]
	v_mfma_f32_16x16x32_bf16 v[12:15], v[160:163], v[218:221], v[12:15]
	v_mfma_f32_16x16x32_bf16 v[80:83], v[48:51], v[198:201], v[80:83]
	v_mfma_f32_16x16x32_bf16 v[76:79], v[172:175], v[198:201], v[76:79]
	v_mfma_f32_16x16x32_bf16 v[64:67], v[48:51], v[206:209], v[64:67]
	v_mfma_f32_16x16x32_bf16 v[60:63], v[172:175], v[206:209], v[60:63]
	v_mfma_f32_16x16x32_bf16 v[40:43], v[48:51], v[214:217], v[40:43]
	v_mfma_f32_16x16x32_bf16 v[34:37], v[172:175], v[214:217], v[34:37]
	v_mfma_f32_16x16x32_bf16 v[16:19], v[48:51], v[222:225], v[16:19]
	v_mfma_f32_16x16x32_bf16 v[12:15], v[172:175], v[222:225], v[12:15]
	v_mfma_f32_16x16x32_bf16 v[56:59], v[176:179], v[202:205], v[56:59]
	v_mfma_f32_16x16x32_bf16 v[52:55], v[186:189], v[202:205], v[52:55]
	v_mfma_f32_16x16x32_bf16 v[24:27], v[176:179], v[210:213], v[24:27]
	v_mfma_f32_16x16x32_bf16 v[20:23], v[186:189], v[210:213], v[20:23]
	v_mfma_f32_16x16x32_bf16 v[8:11], v[176:179], v[218:221], v[8:11]
	v_mfma_f32_16x16x32_bf16 v[4:7], v[186:189], v[218:221], v[4:7]
	v_mfma_f32_16x16x32_bf16 v[44:47], v[176:179], v[194:197], v[72:75]
	v_mfma_f32_16x16x32_bf16 v[48:51], v[186:189], v[194:197], v[68:71]
	v_mfma_f32_16x16x32_bf16 v[56:59], v[180:183], v[206:209], v[56:59]
	v_mfma_f32_16x16x32_bf16 v[52:55], v[190:193], v[206:209], v[52:55]
	v_mfma_f32_16x16x32_bf16 v[24:27], v[180:183], v[214:217], v[24:27]
	v_mfma_f32_16x16x32_bf16 v[20:23], v[190:193], v[214:217], v[20:23]
	v_mfma_f32_16x16x32_bf16 v[8:11], v[180:183], v[222:225], v[8:11]
	v_mfma_f32_16x16x32_bf16 v[4:7], v[190:193], v[222:225], v[4:7]
	v_mfma_f32_16x16x32_bf16 v[44:47], v[180:183], v[198:201], v[44:47]
	v_mfma_f32_16x16x32_bf16 v[48:51], v[190:193], v[198:201], v[48:51]
	s_setprio 0
	s_barrier
	s_add_i32 s3, 0, 0x18000
	v_add_u32_e32 v38, s3, v167
	s_add_i32 s42, 0, 0x1c000
	ds_read_b128 v[68:71], v38
	ds_read_b128 v[72:75], v38 offset:1024
	ds_read_b128 v[160:163], v38 offset:2048
	ds_read_b128 v[172:175], v38 offset:3072
	v_add_u32_e32 v38, s42, v167
	ds_read_b128 v[176:179], v38
	ds_read_b128 v[180:183], v38 offset:1024
	ds_read_b128 v[186:189], v38 offset:2048
	ds_read_b128 v[190:193], v38 offset:3072
	s_add_u32 s30, s30, 0x80000
	s_addc_u32 s31, s31, 0
	s_mov_b32 m0, s52
	v_lshl_add_u64 v[38:39], s[30:31], 0, v[0:1]
	ds_read_b128 v[194:197], v171 offset:32768
	ds_read_b128 v[198:201], v171 offset:33792
	ds_read_b128 v[202:205], v171 offset:34816
	ds_read_b128 v[206:209], v171 offset:35840
	ds_read_b128 v[210:213], v171 offset:36864
	ds_read_b128 v[214:217], v171 offset:37888
	ds_read_b128 v[218:221], v171 offset:38912
	ds_read_b128 v[222:225], v171 offset:39936
	global_load_lds_dwordx4 v[38:39], off
	v_lshl_add_u64 v[38:39], s[30:31], 0, v[148:149]
	s_mov_b32 m0, s53
	s_nop 0
	global_load_lds_dwordx4 v[38:39], off
	s_waitcnt vmcnt(8)
	s_waitcnt lgkmcnt(0)
	s_setprio 1
	s_barrier
	v_mfma_f32_16x16x32_bf16 v[144:147], v[68:71], v[194:197], v[144:147]
	v_mfma_f32_16x16x32_bf16 v[140:143], v[160:163], v[194:197], v[140:143]
	v_mfma_f32_16x16x32_bf16 v[128:131], v[68:71], v[202:205], v[128:131]
	v_mfma_f32_16x16x32_bf16 v[124:127], v[160:163], v[202:205], v[124:127]
	v_mfma_f32_16x16x32_bf16 v[112:115], v[68:71], v[210:213], v[112:115]
	v_mfma_f32_16x16x32_bf16 v[108:111], v[160:163], v[210:213], v[108:111]
	v_mfma_f32_16x16x32_bf16 v[96:99], v[68:71], v[218:221], v[96:99]
	v_mfma_f32_16x16x32_bf16 v[92:95], v[160:163], v[218:221], v[92:95]
	v_mfma_f32_16x16x32_bf16 v[144:147], v[72:75], v[198:201], v[144:147]
	v_mfma_f32_16x16x32_bf16 v[140:143], v[172:175], v[198:201], v[140:143]
	v_mfma_f32_16x16x32_bf16 v[128:131], v[72:75], v[206:209], v[128:131]
	v_mfma_f32_16x16x32_bf16 v[124:127], v[172:175], v[206:209], v[124:127]
	v_mfma_f32_16x16x32_bf16 v[112:115], v[72:75], v[214:217], v[112:115]
	v_mfma_f32_16x16x32_bf16 v[108:111], v[172:175], v[214:217], v[108:111]
	v_mfma_f32_16x16x32_bf16 v[96:99], v[72:75], v[222:225], v[96:99]
	v_mfma_f32_16x16x32_bf16 v[92:95], v[172:175], v[222:225], v[92:95]
	v_mfma_f32_16x16x32_bf16 v[136:139], v[176:179], v[194:197], v[136:139]
	v_mfma_f32_16x16x32_bf16 v[132:135], v[186:189], v[194:197], v[132:135]
	v_mfma_f32_16x16x32_bf16 v[120:123], v[176:179], v[202:205], v[120:123]
	v_mfma_f32_16x16x32_bf16 v[116:119], v[186:189], v[202:205], v[116:119]
	v_mfma_f32_16x16x32_bf16 v[104:107], v[176:179], v[210:213], v[104:107]
	v_mfma_f32_16x16x32_bf16 v[100:103], v[186:189], v[210:213], v[100:103]
	v_mfma_f32_16x16x32_bf16 v[88:91], v[176:179], v[218:221], v[88:91]
	v_mfma_f32_16x16x32_bf16 v[84:87], v[186:189], v[218:221], v[84:87]
	v_mfma_f32_16x16x32_bf16 v[136:139], v[180:183], v[198:201], v[136:139]
	v_mfma_f32_16x16x32_bf16 v[132:135], v[190:193], v[198:201], v[132:135]
	v_mfma_f32_16x16x32_bf16 v[120:123], v[180:183], v[206:209], v[120:123]
	v_mfma_f32_16x16x32_bf16 v[116:119], v[190:193], v[206:209], v[116:119]
	v_mfma_f32_16x16x32_bf16 v[104:107], v[180:183], v[214:217], v[104:107]
	v_mfma_f32_16x16x32_bf16 v[100:103], v[190:193], v[214:217], v[100:103]
	v_mfma_f32_16x16x32_bf16 v[88:91], v[180:183], v[222:225], v[88:91]
	v_mfma_f32_16x16x32_bf16 v[84:87], v[190:193], v[222:225], v[84:87]
	s_setprio 0
	s_barrier
; #define PG8_STAGE(bufoff, gbase, voff) do { _Pragma("unroll") for (int _i = 0; _i < 2; ++_i) \
;         __builtin_amdgcn_global_load_lds((const unsigned*)((const char*)(gbase) + (voff)[_i]), (PG8_LAS unsigned*)(lds + (bufoff) + ldsw + _i * 8192), 16, 0, 0); } while (0)
; #define PG8_LDA(dst, b, h) do { _Pragma("unroll") for (int m = 0; m < 4; ++m) _Pragma("unroll") for (int k = 0; k < 2; ++k) dst[m][k] = *(const PG8_LAS bf16x8*)(lds + PG8_SA(b, h) + aoff + m * 2048 + k * 1024); } while (0)
; #define PG8_MMA(ai, bj, At, Bt) do { __builtin_amdgcn_s_setprio(1); _Pragma("unroll") for (int m = 0; m < 4; ++m) _Pragma("unroll") for (int n = 0; n < 2; ++n) _Pragma("unroll") for (int k = 0; k < 2; ++k) \
;         acc[ai][bj][m][n] = __builtin_amdgcn_mfma_f32_16x16x32_bf16(Bt[n][k], At[m][k], acc[ai][bj][m][n], 0, 0, 0); __builtin_amdgcn_s_setprio(0); } while (0)
; #define PG8_WAIT_V(n) asm volatile("s_waitcnt vmcnt(" #n ")" ::: "memory")
; #define PG8_WAIT_L(n) asm volatile("s_waitcnt lgkmcnt(" #n ")" ::: "memory")
; #define PG8_BAR __builtin_amdgcn_s_barrier()
; #define PG8_SCHED __builtin_amdgcn_sched_barrier(0)
; template <class Epi, class Sched, bool ALIGN_EPI = false, bool SP2 = false>
; __device__ __forceinline__ void gemm_phase(PG8_LAS unsigned char* lds, const Gemm g, const Sched& S, const Epi& E, const int tid) {
;     ...
;             PG8_LDA(At, 1, 1); PG8_STAGE(PG8_SB(1, 0), b3, voffB); PG8_STAGE(PG8_SB(1, 1), b3 + hstep, voffB); PG8_STAGE(PG8_SA(1, 0), a3, voffA);
;             PG8_WAIT_V(8); PG8_WAIT_L(0); PG8_BAR; PG8_MMA(1, 0, At, B0); PG8_MMA(1, 1, At, B1); PG8_BAR; PG8_SCHED;
	s_add_i32 s3, s3, s44
	v_lshl_add_u64 v[38:39], v[164:165], 0, s[46:47]
	s_mov_b32 m0, s3
	ds_read_b128 v[194:197], v171 offset:49152
	ds_read_b128 v[198:201], v171 offset:50176
	ds_read_b128 v[202:205], v171 offset:51200
	ds_read_b128 v[206:209], v171 offset:52224
	ds_read_b128 v[210:213], v171 offset:53248
	ds_read_b128 v[214:217], v171 offset:54272
	ds_read_b128 v[218:221], v171 offset:55296
	ds_read_b128 v[222:225], v171 offset:56320
	global_load_lds_dwordx4 v[38:39], off
	s_add_i32 m0, s3, 0x2000
	s_add_u32 s28, s28, 0x80080
	v_lshl_add_u64 v[38:39], v[226:227], 0, s[46:47]
	s_addc_u32 s29, s29, 0
	s_add_i32 s3, s42, s44
	global_load_lds_dwordx4 v[38:39], off
	v_lshl_add_u64 v[38:39], s[28:29], 0, v[2:3]
	s_mov_b32 m0, s3
	s_nop 0
	global_load_lds_dwordx4 v[38:39], off
	v_lshl_add_u64 v[38:39], s[28:29], 0, v[150:151]
	s_add_i32 m0, s3, 0x2000
	s_nop 0
	global_load_lds_dwordx4 v[38:39], off
	v_lshl_add_u64 v[38:39], v[228:229], 0, s[46:47]
	s_mov_b32 m0, s5
	s_nop 0
	global_load_lds_dwordx4 v[38:39], off
	v_lshl_add_u64 v[38:39], v[230:231], 0, s[46:47]
	s_mov_b32 m0, s54
	s_nop 0
	global_load_lds_dwordx4 v[38:39], off
	s_waitcnt vmcnt(8)
	s_waitcnt lgkmcnt(0)
	s_setprio 1
	s_barrier
	v_mfma_f32_16x16x32_bf16 v[80:83], v[68:71], v[194:197], v[80:83]
	v_mfma_f32_16x16x32_bf16 v[76:79], v[160:163], v[194:197], v[76:79]
	v_mfma_f32_16x16x32_bf16 v[64:67], v[68:71], v[202:205], v[64:67]
	v_mfma_f32_16x16x32_bf16 v[60:63], v[160:163], v[202:205], v[60:63]
	v_mfma_f32_16x16x32_bf16 v[38:41], v[68:71], v[210:213], v[40:43]
	v_mfma_f32_16x16x32_bf16 v[34:37], v[160:163], v[210:213], v[34:37]
	v_mfma_f32_16x16x32_bf16 v[16:19], v[68:71], v[218:221], v[16:19]
	v_mfma_f32_16x16x32_bf16 v[12:15], v[160:163], v[218:221], v[12:15]
	v_mfma_f32_16x16x32_bf16 v[80:83], v[72:75], v[198:201], v[80:83]
	v_mfma_f32_16x16x32_bf16 v[76:79], v[172:175], v[198:201], v[76:79]
	v_mfma_f32_16x16x32_bf16 v[64:67], v[72:75], v[206:209], v[64:67]
	v_mfma_f32_16x16x32_bf16 v[60:63], v[172:175], v[206:209], v[60:63]
	v_mfma_f32_16x16x32_bf16 v[40:43], v[72:75], v[214:217], v[38:41]
	v_mfma_f32_16x16x32_bf16 v[36:39], v[172:175], v[214:217], v[34:37]
	v_mfma_f32_16x16x32_bf16 v[16:19], v[72:75], v[222:225], v[16:19]
	v_mfma_f32_16x16x32_bf16 v[12:15], v[172:175], v[222:225], v[12:15]
	v_mfma_f32_16x16x32_bf16 v[44:47], v[176:179], v[194:197], v[44:47]
	v_mfma_f32_16x16x32_bf16 v[72:75], v[180:183], v[198:201], v[44:47]
	v_mfma_f32_16x16x32_bf16 v[44:47], v[186:189], v[194:197], v[48:51]
	v_mfma_f32_16x16x32_bf16 v[68:71], v[190:193], v[198:201], v[44:47]
	v_mfma_f32_16x16x32_bf16 v[44:47], v[176:179], v[202:205], v[56:59]
	v_mfma_f32_16x16x32_bf16 v[56:59], v[180:183], v[206:209], v[44:47]
	v_mfma_f32_16x16x32_bf16 v[44:47], v[186:189], v[202:205], v[52:55]
	v_mfma_f32_16x16x32_bf16 v[24:27], v[176:179], v[210:213], v[24:27]
	v_mfma_f32_16x16x32_bf16 v[20:23], v[186:189], v[210:213], v[20:23]
	v_mfma_f32_16x16x32_bf16 v[8:11], v[176:179], v[218:221], v[8:11]
	v_mfma_f32_16x16x32_bf16 v[4:7], v[186:189], v[218:221], v[4:7]
	v_mfma_f32_16x16x32_bf16 v[52:55], v[190:193], v[206:209], v[44:47]
	v_mfma_f32_16x16x32_bf16 v[24:27], v[180:183], v[214:217], v[24:27]
	v_mfma_f32_16x16x32_bf16 v[20:23], v[190:193], v[214:217], v[20:23]
	v_mfma_f32_16x16x32_bf16 v[8:11], v[180:183], v[222:225], v[8:11]
	v_mfma_f32_16x16x32_bf16 v[4:7], v[190:193], v[222:225], v[4:7]
	s_setprio 0
	s_barrier
	s_add_i32 s50, s50, 2
	s_add_u32 s26, s26, 0x100
	s_addc_u32 s27, s27, 0
	s_add_u32 s23, s23, 0x100
	s_addc_u32 s25, s25, 0
	s_cmp_gt_u32 s50, 29
	s_cbranch_scc1 .LBB0_159

; #define PG8_STAGE(bufoff, gbase, voff) do { _Pragma("unroll") for (int _i = 0; _i < 2; ++_i) \
;         __builtin_amdgcn_global_load_lds((const unsigned*)((const char*)(gbase) + (voff)[_i]), (PG8_LAS unsigned*)(lds + (bufoff) + ldsw + _i * 8192), 16, 0, 0); } while (0)
; #define PG8_LDA(dst, b, h) do { _Pragma("unroll") for (int m = 0; m < 4; ++m) _Pragma("unroll") for (int k = 0; k < 2; ++k) dst[m][k] = *(const PG8_LAS bf16x8*)(lds + PG8_SA(b, h) + aoff + m * 2048 + k * 1024); } while (0)
; #define PG8_LDB(dst, b, h) do { _Pragma("unroll") for (int n = 0; n < 2; ++n) _Pragma("unroll") for (int k = 0; k < 2; ++k) dst[n][k] = *(const PG8_LAS bf16x8*)(lds + PG8_SB(b, h) + boff + n * 2048 + k * 1024); } while (0)
; #define PG8_MMA(ai, bj, At, Bt) do { __builtin_amdgcn_s_setprio(1); _Pragma("unroll") for (int m = 0; m < 4; ++m) _Pragma("unroll") for (int n = 0; n < 2; ++n) _Pragma("unroll") for (int k = 0; k < 2; ++k) \
;         acc[ai][bj][m][n] = __builtin_amdgcn_mfma_f32_16x16x32_bf16(Bt[n][k], At[m][k], acc[ai][bj][m][n], 0, 0, 0); __builtin_amdgcn_s_setprio(0); } while (0)
; #define PG8_WAIT_V(n) asm volatile("s_waitcnt vmcnt(" #n ")" ::: "memory")
; #define PG8_WAIT_L(n) asm volatile("s_waitcnt lgkmcnt(" #n ")" ::: "memory")
; #define PG8_BAR __builtin_amdgcn_s_barrier()
; #define PG8_SCHED __builtin_amdgcn_sched_barrier(0)
; template <class Epi, class Sched, bool ALIGN_EPI = false, bool SP2 = false>
; __device__ __forceinline__ void gemm_phase(PG8_LAS unsigned char* lds, const Gemm g, const Sched& S, const Epi& E, const int tid) {
;     ...
;             const char* a1 = cA + (size_t)(t + 1) * kstep;
;             const char* a2 = last ? nA : cA + (size_t)(t + 2) * kstep; const char* b2 = last ? nB : cB + (size_t)(t + 2) * kstep;
;             const char* a3 = a2 + kstep; const char* b3 = b2 + kstep;
;             if (last && has_next) S.a_ready(nxt);
;             if (last) E.prefetch(lds + EPI_LDS_OFF + wid * 1024, cur, wr, wc, lane);
;             if constexpr (SP2) {
;             PG8_LDB(B0, 0, 0); PG8_LDB(B1, 0, 1); PG8_SCHED; PG8_LDA(At, 0, 0); PG8_STAGE(PG8_SA(1, 1), a1 + hstep, voffA);
;             PG8_WAIT_V(8); PG8_WAIT_L(0); PG8_BAR; PG8_MMA(0, 0, At, B0); PG8_MMA(0, 1, At, B1); PG8_BAR; PG8_SCHED;
;             PG8_LDA(At, 0, 1); PG8_STAGE(PG8_SB(0, 0), b2, voffB); PG8_STAGE(PG8_SB(0, 1), b2 + hstep, voffB); PG8_STAGE(PG8_SA(0, 0), a2, voffA);
.LBB0_228:
	s_add_u32 s22, s20, 0x100
	s_addc_u32 s23, s21, 0
	s_and_b64 s[24:25], s[24:25], exec
	s_cselect_b32 s27, s11, s23
	s_cselect_b32 s26, s10, s22
	s_cselect_b32 s25, s17, s75
	s_cselect_b32 s24, s16, s74
	s_add_i32 s42, 0, 0x10000
	s_add_i32 s43, 0, 0x14000
	v_add_u32_e32 v146, s42, v220
	v_add_u32_e32 v162, s43, v220
	ds_read_b128 v[134:137], v146
	ds_read_b128 v[138:141], v146 offset:1024
	ds_read_b128 v[142:145], v146 offset:2048
	ds_read_b128 v[146:149], v146 offset:3072
	ds_read_b128 v[150:153], v162
	ds_read_b128 v[154:157], v162 offset:1024
	ds_read_b128 v[158:161], v162 offset:2048
	ds_read_b128 v[172:175], v162 offset:3072
	v_lshl_add_u64 v[162:163], s[20:21], 0, v[168:169]
	s_add_i32 m0, s30, 0xc000
	ds_read_b128 v[176:179], v226
	ds_read_b128 v[186:189], v226 offset:1024
	ds_read_b128 v[190:193], v226 offset:2048
	ds_read_b128 v[194:197], v226 offset:3072
	ds_read_b128 v[198:201], v226 offset:4096
	ds_read_b128 v[202:205], v226 offset:5120
	ds_read_b128 v[206:209], v226 offset:6144
	ds_read_b128 v[210:213], v226 offset:7168
	global_load_lds_dwordx4 v[162:163], off
	v_lshl_add_u64 v[162:163], s[20:21], 0, v[170:171]
	s_add_i32 m0, s30, 0xe000
	s_nop 0
	global_load_lds_dwordx4 v[162:163], off
	s_waitcnt vmcnt(8)
	s_waitcnt lgkmcnt(0)
	s_setprio 1
	s_barrier
	v_mfma_f32_16x16x32_bf16 v[128:131], v[134:137], v[176:179], v[128:131]
	v_mfma_f32_16x16x32_bf16 v[124:127], v[142:145], v[176:179], v[124:127]
	v_mfma_f32_16x16x32_bf16 v[112:115], v[134:137], v[190:193], v[112:115]
	v_mfma_f32_16x16x32_bf16 v[108:111], v[142:145], v[190:193], v[108:111]
	v_mfma_f32_16x16x32_bf16 v[96:99], v[134:137], v[198:201], v[96:99]
	v_mfma_f32_16x16x32_bf16 v[92:95], v[142:145], v[198:201], v[92:95]
	v_mfma_f32_16x16x32_bf16 v[80:83], v[134:137], v[206:209], v[80:83]
	v_mfma_f32_16x16x32_bf16 v[76:79], v[142:145], v[206:209], v[76:79]
	v_mfma_f32_16x16x32_bf16 v[128:131], v[138:141], v[186:189], v[128:131]
	v_mfma_f32_16x16x32_bf16 v[124:127], v[146:149], v[186:189], v[124:127]
	v_mfma_f32_16x16x32_bf16 v[112:115], v[138:141], v[194:197], v[112:115]
	v_mfma_f32_16x16x32_bf16 v[108:111], v[146:149], v[194:197], v[108:111]
	v_mfma_f32_16x16x32_bf16 v[96:99], v[138:141], v[202:205], v[96:99]
	v_mfma_f32_16x16x32_bf16 v[92:95], v[146:149], v[202:205], v[92:95]
	v_mfma_f32_16x16x32_bf16 v[80:83], v[138:141], v[210:213], v[80:83]
	v_mfma_f32_16x16x32_bf16 v[76:79], v[146:149], v[210:213], v[76:79]
	v_mfma_f32_16x16x32_bf16 v[120:123], v[150:153], v[176:179], v[120:123]
	v_mfma_f32_16x16x32_bf16 v[116:119], v[158:161], v[176:179], v[116:119]
	v_mfma_f32_16x16x32_bf16 v[104:107], v[150:153], v[190:193], v[104:107]
	v_mfma_f32_16x16x32_bf16 v[100:103], v[158:161], v[190:193], v[100:103]
	v_mfma_f32_16x16x32_bf16 v[88:91], v[150:153], v[198:201], v[88:91]
	v_mfma_f32_16x16x32_bf16 v[84:87], v[158:161], v[198:201], v[84:87]
	v_mfma_f32_16x16x32_bf16 v[72:75], v[150:153], v[206:209], v[72:75]
	v_mfma_f32_16x16x32_bf16 v[68:71], v[158:161], v[206:209], v[68:71]
	v_mfma_f32_16x16x32_bf16 v[120:123], v[154:157], v[186:189], v[120:123]
	v_mfma_f32_16x16x32_bf16 v[116:119], v[172:175], v[186:189], v[116:119]
	v_mfma_f32_16x16x32_bf16 v[104:107], v[154:157], v[194:197], v[104:107]
	v_mfma_f32_16x16x32_bf16 v[100:103], v[172:175], v[194:197], v[100:103]
	v_mfma_f32_16x16x32_bf16 v[88:91], v[154:157], v[202:205], v[88:91]
	v_mfma_f32_16x16x32_bf16 v[84:87], v[172:175], v[202:205], v[84:87]
	v_mfma_f32_16x16x32_bf16 v[72:75], v[154:157], v[210:213], v[72:75]
	v_mfma_f32_16x16x32_bf16 v[68:71], v[172:175], v[210:213], v[68:71]
	s_setprio 0
	s_barrier
	s_add_i32 s20, s42, s29
	v_lshl_add_u64 v[162:163], s[24:25], 0, v[2:3]
	s_mov_b32 m0, s20
	ds_read_b128 v[176:179], v226 offset:16384
	ds_read_b128 v[186:189], v226 offset:17408
	ds_read_b128 v[190:193], v226 offset:18432
	ds_read_b128 v[194:197], v226 offset:19456
	ds_read_b128 v[198:201], v226 offset:20480
	ds_read_b128 v[202:205], v226 offset:21504
	ds_read_b128 v[206:209], v226 offset:22528
	ds_read_b128 v[210:213], v226 offset:23552
	global_load_lds_dwordx4 v[162:163], off
	s_add_i32 m0, s20, 0x2000
	s_add_u32 s20, s24, 0x160000
	v_lshl_add_u64 v[180:181], s[24:25], 0, v[166:167]
	s_addc_u32 s21, s25, 0
	s_add_i32 s42, s43, s29
	global_load_lds_dwordx4 v[180:181], off
	v_lshl_add_u64 v[182:183], s[20:21], 0, v[2:3]
	s_mov_b32 m0, s42
	v_lshl_add_u64 v[214:215], s[26:27], 0, v[164:165]
	global_load_lds_dwordx4 v[182:183], off
	v_lshl_add_u64 v[182:183], s[20:21], 0, v[166:167]
	s_add_i32 m0, s42, 0x2000
	s_nop 0
	global_load_lds_dwordx4 v[182:183], off
	v_lshl_add_u64 v[182:183], s[26:27], 0, v[0:1]
	s_mov_b32 m0, s30
	s_nop 0
	global_load_lds_dwordx4 v[182:183], off
	s_mov_b32 m0, s31
	s_nop 0
	global_load_lds_dwordx4 v[214:215], off
	s_waitcnt vmcnt(8)
	s_waitcnt lgkmcnt(0)
	s_setprio 1
	s_barrier
; #define PG8_STAGE(bufoff, gbase, voff) do { _Pragma("unroll") for (int _i = 0; _i < 2; ++_i) \
;         __builtin_amdgcn_global_load_lds((const unsigned*)((const char*)(gbase) + (voff)[_i]), (PG8_LAS unsigned*)(lds + (bufoff) + ldsw + _i * 8192), 16, 0, 0); } while (0)
; #define PG8_LDA(dst, b, h) do { _Pragma("unroll") for (int m = 0; m < 4; ++m) _Pragma("unroll") for (int k = 0; k < 2; ++k) dst[m][k] = *(const PG8_LAS bf16x8*)(lds + PG8_SA(b, h) + aoff + m * 2048 + k * 1024); } while (0)
; #define PG8_LDB(dst, b, h) do { _Pragma("unroll") for (int n = 0; n < 2; ++n) _Pragma("unroll") for (int k = 0; k < 2; ++k) dst[n][k] = *(const PG8_LAS bf16x8*)(lds + PG8_SB(b, h) + boff + n * 2048 + k * 1024); } while (0)
; #define PG8_MMA(ai, bj, At, Bt) do { __builtin_amdgcn_s_setprio(1); _Pragma("unroll") for (int m = 0; m < 4; ++m) _Pragma("unroll") for (int n = 0; n < 2; ++n) _Pragma("unroll") for (int k = 0; k < 2; ++k) \
;         acc[ai][bj][m][n] = __builtin_amdgcn_mfma_f32_16x16x32_bf16(Bt[n][k], At[m][k], acc[ai][bj][m][n], 0, 0, 0); __builtin_amdgcn_s_setprio(0); } while (0)
; #define PG8_WAIT_V(n) asm volatile("s_waitcnt vmcnt(" #n ")" ::: "memory")
; #define PG8_WAIT_L(n) asm volatile("s_waitcnt lgkmcnt(" #n ")" ::: "memory")
; #define PG8_BAR __builtin_amdgcn_s_barrier()
; #define PG8_SCHED __builtin_amdgcn_sched_barrier(0)
; template <class Epi, class Sched, bool ALIGN_EPI = false, bool SP2 = false>
; __device__ __forceinline__ void gemm_phase(PG8_LAS unsigned char* lds, const Gemm g, const Sched& S, const Epi& E, const int tid) {
;     ...
;             PG8_WAIT_V(8); PG8_WAIT_L(0); PG8_BAR; PG8_MMA(1, 0, At, B0); PG8_MMA(1, 1, At, B1); PG8_BAR; PG8_SCHED;
;             PG8_LDB(B0, 1, 0); PG8_LDB(B1, 1, 1); PG8_SCHED; PG8_LDA(At, 1, 0); PG8_STAGE(PG8_SA(0, 1), a2 + hstep, voffA);
;             PG8_WAIT_V(8); PG8_WAIT_L(0); PG8_BAR; PG8_MMA(0, 0, At, B0); PG8_MMA(0, 1, At, B1); PG8_BAR; PG8_SCHED;
	v_mfma_f32_16x16x32_bf16 v[64:67], v[134:137], v[176:179], v[64:67]
	v_mfma_f32_16x16x32_bf16 v[60:63], v[142:145], v[176:179], v[60:63]
	v_mfma_f32_16x16x32_bf16 v[48:51], v[134:137], v[190:193], v[48:51]
	v_mfma_f32_16x16x32_bf16 v[44:47], v[142:145], v[190:193], v[44:47]
	v_mfma_f32_16x16x32_bf16 v[32:35], v[134:137], v[198:201], v[32:35]
	v_mfma_f32_16x16x32_bf16 v[28:31], v[142:145], v[198:201], v[28:31]
	v_mfma_f32_16x16x32_bf16 v[16:19], v[134:137], v[206:209], v[16:19]
	v_mfma_f32_16x16x32_bf16 v[12:15], v[142:145], v[206:209], v[12:15]
	v_mfma_f32_16x16x32_bf16 v[64:67], v[138:141], v[186:189], v[64:67]
	v_mfma_f32_16x16x32_bf16 v[60:63], v[146:149], v[186:189], v[60:63]
	v_mfma_f32_16x16x32_bf16 v[48:51], v[138:141], v[194:197], v[48:51]
	v_mfma_f32_16x16x32_bf16 v[44:47], v[146:149], v[194:197], v[44:47]
	v_mfma_f32_16x16x32_bf16 v[32:35], v[138:141], v[202:205], v[32:35]
	v_mfma_f32_16x16x32_bf16 v[28:31], v[146:149], v[202:205], v[28:31]
	v_mfma_f32_16x16x32_bf16 v[16:19], v[138:141], v[210:213], v[16:19]
	v_mfma_f32_16x16x32_bf16 v[12:15], v[146:149], v[210:213], v[12:15]
	v_mfma_f32_16x16x32_bf16 v[56:59], v[150:153], v[176:179], v[56:59]
	v_mfma_f32_16x16x32_bf16 v[52:55], v[158:161], v[176:179], v[52:55]
	v_mfma_f32_16x16x32_bf16 v[40:43], v[150:153], v[190:193], v[40:43]
	v_mfma_f32_16x16x32_bf16 v[36:39], v[158:161], v[190:193], v[36:39]
	v_mfma_f32_16x16x32_bf16 v[24:27], v[150:153], v[198:201], v[24:27]
	v_mfma_f32_16x16x32_bf16 v[20:23], v[158:161], v[198:201], v[20:23]
	v_mfma_f32_16x16x32_bf16 v[8:11], v[150:153], v[206:209], v[8:11]
	v_mfma_f32_16x16x32_bf16 v[4:7], v[158:161], v[206:209], v[4:7]
	v_mfma_f32_16x16x32_bf16 v[56:59], v[154:157], v[186:189], v[56:59]
	v_mfma_f32_16x16x32_bf16 v[52:55], v[172:175], v[186:189], v[52:55]
	v_mfma_f32_16x16x32_bf16 v[40:43], v[154:157], v[194:197], v[40:43]
	v_mfma_f32_16x16x32_bf16 v[36:39], v[172:175], v[194:197], v[36:39]
	v_mfma_f32_16x16x32_bf16 v[24:27], v[154:157], v[202:205], v[24:27]
	v_mfma_f32_16x16x32_bf16 v[20:23], v[172:175], v[202:205], v[20:23]
	v_mfma_f32_16x16x32_bf16 v[8:11], v[154:157], v[210:213], v[8:11]
	v_mfma_f32_16x16x32_bf16 v[4:7], v[172:175], v[210:213], v[4:7]
	s_setprio 0
	s_barrier
	s_add_i32 s42, 0, 0x18000
	s_add_i32 s43, 0, 0x1c000
	v_add_u32_e32 v146, s42, v220
	v_add_u32_e32 v172, s43, v220
	ds_read_b128 v[134:137], v146
	ds_read_b128 v[138:141], v146 offset:1024
	ds_read_b128 v[142:145], v146 offset:2048
	ds_read_b128 v[146:149], v146 offset:3072
	ds_read_b128 v[150:153], v172
	ds_read_b128 v[154:157], v172 offset:1024
	ds_read_b128 v[158:161], v172 offset:2048
	ds_read_b128 v[172:175], v172 offset:3072
	s_add_u32 s20, s26, 0x160000
	s_addc_u32 s21, s27, 0
	s_mov_b32 m0, s36
	v_lshl_add_u64 v[216:217], s[20:21], 0, v[0:1]
	ds_read_b128 v[176:179], v226 offset:32768
	ds_read_b128 v[186:189], v226 offset:33792
	ds_read_b128 v[190:193], v226 offset:34816
	ds_read_b128 v[194:197], v226 offset:35840
	ds_read_b128 v[198:201], v226 offset:36864
	ds_read_b128 v[202:205], v226 offset:37888
	ds_read_b128 v[206:209], v226 offset:38912
	ds_read_b128 v[210:213], v226 offset:39936
	global_load_lds_dwordx4 v[216:217], off
	v_lshl_add_u64 v[216:217], s[20:21], 0, v[164:165]
	s_mov_b32 m0, s37
	s_nop 0
	global_load_lds_dwordx4 v[216:217], off
	s_waitcnt vmcnt(8)
	s_waitcnt lgkmcnt(0)
	s_setprio 1
	s_barrier
	v_mfma_f32_16x16x32_bf16 v[128:131], v[134:137], v[176:179], v[128:131]
	v_mfma_f32_16x16x32_bf16 v[124:127], v[142:145], v[176:179], v[124:127]
	v_mfma_f32_16x16x32_bf16 v[112:115], v[134:137], v[190:193], v[112:115]
	v_mfma_f32_16x16x32_bf16 v[108:111], v[142:145], v[190:193], v[108:111]
	v_mfma_f32_16x16x32_bf16 v[96:99], v[134:137], v[198:201], v[96:99]
	v_mfma_f32_16x16x32_bf16 v[92:95], v[142:145], v[198:201], v[92:95]
	v_mfma_f32_16x16x32_bf16 v[80:83], v[134:137], v[206:209], v[80:83]
	v_mfma_f32_16x16x32_bf16 v[76:79], v[142:145], v[206:209], v[76:79]
	v_mfma_f32_16x16x32_bf16 v[128:131], v[138:141], v[186:189], v[128:131]
	v_mfma_f32_16x16x32_bf16 v[124:127], v[146:149], v[186:189], v[124:127]
	v_mfma_f32_16x16x32_bf16 v[112:115], v[138:141], v[194:197], v[112:115]
	v_mfma_f32_16x16x32_bf16 v[108:111], v[146:149], v[194:197], v[108:111]
	v_mfma_f32_16x16x32_bf16 v[96:99], v[138:141], v[202:205], v[96:99]
	v_mfma_f32_16x16x32_bf16 v[92:95], v[146:149], v[202:205], v[92:95]
	v_mfma_f32_16x16x32_bf16 v[80:83], v[138:141], v[210:213], v[80:83]
	v_mfma_f32_16x16x32_bf16 v[76:79], v[146:149], v[210:213], v[76:79]
	v_mfma_f32_16x16x32_bf16 v[120:123], v[150:153], v[176:179], v[120:123]
	v_mfma_f32_16x16x32_bf16 v[116:119], v[158:161], v[176:179], v[116:119]
	v_mfma_f32_16x16x32_bf16 v[104:107], v[150:153], v[190:193], v[104:107]
	v_mfma_f32_16x16x32_bf16 v[100:103], v[158:161], v[190:193], v[100:103]
	v_mfma_f32_16x16x32_bf16 v[88:91], v[150:153], v[198:201], v[88:91]
	v_mfma_f32_16x16x32_bf16 v[84:87], v[158:161], v[198:201], v[84:87]
	v_mfma_f32_16x16x32_bf16 v[72:75], v[150:153], v[206:209], v[72:75]
	v_mfma_f32_16x16x32_bf16 v[68:71], v[158:161], v[206:209], v[68:71]
	v_mfma_f32_16x16x32_bf16 v[120:123], v[154:157], v[186:189], v[120:123]
	v_mfma_f32_16x16x32_bf16 v[116:119], v[172:175], v[186:189], v[116:119]
	v_mfma_f32_16x16x32_bf16 v[104:107], v[154:157], v[194:197], v[104:107]
	v_mfma_f32_16x16x32_bf16 v[100:103], v[172:175], v[194:197], v[100:103]
	v_mfma_f32_16x16x32_bf16 v[88:91], v[154:157], v[202:205], v[88:91]
	v_mfma_f32_16x16x32_bf16 v[84:87], v[172:175], v[202:205], v[84:87]
	v_mfma_f32_16x16x32_bf16 v[72:75], v[154:157], v[210:213], v[72:75]
	v_mfma_f32_16x16x32_bf16 v[68:71], v[172:175], v[210:213], v[68:71]
	s_setprio 0
	s_barrier
; #define PG8_STAGE(bufoff, gbase, voff) do { _Pragma("unroll") for (int _i = 0; _i < 2; ++_i) \
;         __builtin_amdgcn_global_load_lds((const unsigned*)((const char*)(gbase) + (voff)[_i]), (PG8_LAS unsigned*)(lds + (bufoff) + ldsw + _i * 8192), 16, 0, 0); } while (0)
; #define PG8_LDA(dst, b, h) do { _Pragma("unroll") for (int m = 0; m < 4; ++m) _Pragma("unroll") for (int k = 0; k < 2; ++k) dst[m][k] = *(const PG8_LAS bf16x8*)(lds + PG8_SA(b, h) + aoff + m * 2048 + k * 1024); } while (0)
; #define PG8_MMA(ai, bj, At, Bt) do { __builtin_amdgcn_s_setprio(1); _Pragma("unroll") for (int m = 0; m < 4; ++m) _Pragma("unroll") for (int n = 0; n < 2; ++n) _Pragma("unroll") for (int k = 0; k < 2; ++k) \
;         acc[ai][bj][m][n] = __builtin_amdgcn_mfma_f32_16x16x32_bf16(Bt[n][k], At[m][k], acc[ai][bj][m][n], 0, 0, 0); __builtin_amdgcn_s_setprio(0); } while (0)
; #define PG8_WAIT_V(n) asm volatile("s_waitcnt vmcnt(" #n ")" ::: "memory")
; #define PG8_WAIT_L(n) asm volatile("s_waitcnt lgkmcnt(" #n ")" ::: "memory")
; #define PG8_BAR __builtin_amdgcn_s_barrier()
; #define PG8_SCHED __builtin_amdgcn_sched_barrier(0)
; template <class Epi, class Sched, bool ALIGN_EPI = false, bool SP2 = false>
; __device__ __forceinline__ void gemm_phase(PG8_LAS unsigned char* lds, const Gemm g, const Sched& S, const Epi& E, const int tid) {
;     ...
;             PG8_LDA(At, 1, 1); PG8_STAGE(PG8_SB(1, 0), b3, voffB); PG8_STAGE(PG8_SB(1, 1), b3 + hstep, voffB); PG8_STAGE(PG8_SA(1, 0), a3, voffA);
;             PG8_WAIT_V(8); PG8_WAIT_L(0); PG8_BAR; PG8_MMA(1, 0, At, B0); PG8_MMA(1, 1, At, B1); PG8_BAR; PG8_SCHED;
	s_add_i32 s20, s42, s29
	v_lshl_add_u64 v[162:163], v[162:163], 0, s[46:47]
	s_mov_b32 m0, s20
	ds_read_b128 v[176:179], v226 offset:49152
	ds_read_b128 v[186:189], v226 offset:50176
	ds_read_b128 v[190:193], v226 offset:51200
	ds_read_b128 v[194:197], v226 offset:52224
	ds_read_b128 v[198:201], v226 offset:53248
	ds_read_b128 v[202:205], v226 offset:54272
	ds_read_b128 v[206:209], v226 offset:55296
	ds_read_b128 v[210:213], v226 offset:56320
	global_load_lds_dwordx4 v[162:163], off
	s_add_i32 m0, s20, 0x2000
	s_add_u32 s20, s24, 0x160080
	v_lshl_add_u64 v[162:163], v[180:181], 0, s[46:47]
	s_addc_u32 s21, s25, 0
	s_add_i32 s24, s43, s29
	global_load_lds_dwordx4 v[162:163], off
	v_lshl_add_u64 v[162:163], s[20:21], 0, v[2:3]
	s_mov_b32 m0, s24
	s_nop 0
	global_load_lds_dwordx4 v[162:163], off
	v_lshl_add_u64 v[162:163], s[20:21], 0, v[166:167]
	s_add_i32 m0, s24, 0x2000
	s_nop 0
	global_load_lds_dwordx4 v[162:163], off
	v_lshl_add_u64 v[162:163], v[182:183], 0, s[46:47]
	s_mov_b32 m0, s39
	s_nop 0
	global_load_lds_dwordx4 v[162:163], off
	v_lshl_add_u64 v[162:163], v[214:215], 0, s[46:47]
	s_mov_b32 m0, s44
	s_nop 0
	global_load_lds_dwordx4 v[162:163], off
	s_waitcnt vmcnt(8)
	s_waitcnt lgkmcnt(0)
	s_setprio 1
	s_barrier
	v_mfma_f32_16x16x32_bf16 v[64:67], v[134:137], v[176:179], v[64:67]
	v_mfma_f32_16x16x32_bf16 v[60:63], v[142:145], v[176:179], v[60:63]
	v_mfma_f32_16x16x32_bf16 v[48:51], v[134:137], v[190:193], v[48:51]
	v_mfma_f32_16x16x32_bf16 v[44:47], v[142:145], v[190:193], v[44:47]
	v_mfma_f32_16x16x32_bf16 v[32:35], v[134:137], v[198:201], v[32:35]
	v_mfma_f32_16x16x32_bf16 v[28:31], v[142:145], v[198:201], v[28:31]
	v_mfma_f32_16x16x32_bf16 v[16:19], v[134:137], v[206:209], v[16:19]
	v_mfma_f32_16x16x32_bf16 v[12:15], v[142:145], v[206:209], v[12:15]
	v_mfma_f32_16x16x32_bf16 v[64:67], v[138:141], v[186:189], v[64:67]
	v_mfma_f32_16x16x32_bf16 v[60:63], v[146:149], v[186:189], v[60:63]
	v_mfma_f32_16x16x32_bf16 v[48:51], v[138:141], v[194:197], v[48:51]
	v_mfma_f32_16x16x32_bf16 v[44:47], v[146:149], v[194:197], v[44:47]
	v_mfma_f32_16x16x32_bf16 v[32:35], v[138:141], v[202:205], v[32:35]
	v_mfma_f32_16x16x32_bf16 v[28:31], v[146:149], v[202:205], v[28:31]
	v_mfma_f32_16x16x32_bf16 v[16:19], v[138:141], v[210:213], v[16:19]
	v_mfma_f32_16x16x32_bf16 v[12:15], v[146:149], v[210:213], v[12:15]
	v_mfma_f32_16x16x32_bf16 v[56:59], v[150:153], v[176:179], v[56:59]
	v_mfma_f32_16x16x32_bf16 v[52:55], v[158:161], v[176:179], v[52:55]
	v_mfma_f32_16x16x32_bf16 v[40:43], v[150:153], v[190:193], v[40:43]
	v_mfma_f32_16x16x32_bf16 v[36:39], v[158:161], v[190:193], v[36:39]
	v_mfma_f32_16x16x32_bf16 v[24:27], v[150:153], v[198:201], v[24:27]
	v_mfma_f32_16x16x32_bf16 v[20:23], v[158:161], v[198:201], v[20:23]
	v_mfma_f32_16x16x32_bf16 v[8:11], v[150:153], v[206:209], v[8:11]
	v_mfma_f32_16x16x32_bf16 v[4:7], v[158:161], v[206:209], v[4:7]
	v_mfma_f32_16x16x32_bf16 v[56:59], v[154:157], v[186:189], v[56:59]
	v_mfma_f32_16x16x32_bf16 v[52:55], v[172:175], v[186:189], v[52:55]
	v_mfma_f32_16x16x32_bf16 v[40:43], v[154:157], v[194:197], v[40:43]
	v_mfma_f32_16x16x32_bf16 v[36:39], v[172:175], v[194:197], v[36:39]
	v_mfma_f32_16x16x32_bf16 v[24:27], v[154:157], v[202:205], v[24:27]
	v_mfma_f32_16x16x32_bf16 v[20:23], v[172:175], v[202:205], v[20:23]
	v_mfma_f32_16x16x32_bf16 v[8:11], v[154:157], v[210:213], v[8:11]
	v_mfma_f32_16x16x32_bf16 v[4:7], v[172:175], v[210:213], v[4:7]
	s_setprio 0
	s_barrier
	s_add_i32 s84, s84, 2
	s_add_u32 s74, s74, 0x100
	s_addc_u32 s75, s75, 0
	s_cmpk_gt_u32 s84, 0x55
	s_mov_b64 s[20:21], s[22:23]
	s_cbranch_scc1 .LBB0_231

; #define PG8_STAGE(bufoff, gbase, voff) do { _Pragma("unroll") for (int _i = 0; _i < 2; ++_i) \
;         __builtin_amdgcn_global_load_lds((const unsigned*)((const char*)(gbase) + (voff)[_i]), (PG8_LAS unsigned*)(lds + (bufoff) + ldsw + _i * 8192), 16, 0, 0); } while (0)
; #define PG8_LDA(dst, b, h) do { _Pragma("unroll") for (int m = 0; m < 4; ++m) _Pragma("unroll") for (int k = 0; k < 2; ++k) dst[m][k] = *(const PG8_LAS bf16x8*)(lds + PG8_SA(b, h) + aoff + m * 2048 + k * 1024); } while (0)
; #define PG8_LDB(dst, b, h) do { _Pragma("unroll") for (int n = 0; n < 2; ++n) _Pragma("unroll") for (int k = 0; k < 2; ++k) dst[n][k] = *(const PG8_LAS bf16x8*)(lds + PG8_SB(b, h) + boff + n * 2048 + k * 1024); } while (0)
; #define PG8_MMA(ai, bj, At, Bt) do { __builtin_amdgcn_s_setprio(1); _Pragma("unroll") for (int m = 0; m < 4; ++m) _Pragma("unroll") for (int n = 0; n < 2; ++n) _Pragma("unroll") for (int k = 0; k < 2; ++k) \
;         acc[ai][bj][m][n] = __builtin_amdgcn_mfma_f32_16x16x32_bf16(Bt[n][k], At[m][k], acc[ai][bj][m][n], 0, 0, 0); __builtin_amdgcn_s_setprio(0); } while (0)
; #define PG8_WAIT_V(n) asm volatile("s_waitcnt vmcnt(" #n ")" ::: "memory")
; #define PG8_WAIT_L(n) asm volatile("s_waitcnt lgkmcnt(" #n ")" ::: "memory")
; #define PG8_BAR __builtin_amdgcn_s_barrier()
; #define PG8_SCHED __builtin_amdgcn_sched_barrier(0)
; template <class Epi, class Sched, bool ALIGN_EPI = false, bool SP2 = false>
; __device__ __forceinline__ void gemm_phase(PG8_LAS unsigned char* lds, const Gemm g, const Sched& S, const Epi& E, const int tid) {
;     ...
;             const char* a1 = cA + (size_t)(t + 1) * kstep;
;             const char* a2 = last ? nA : cA + (size_t)(t + 2) * kstep; const char* b2 = last ? nB : cB + (size_t)(t + 2) * kstep;
;             const char* a3 = a2 + kstep; const char* b3 = b2 + kstep;
;             if (last && has_next) S.a_ready(nxt);
;             if (last) E.prefetch(lds + EPI_LDS_OFF + wid * 1024, cur, wr, wc, lane);
;             if constexpr (SP2) {
;             PG8_LDB(B0, 0, 0); PG8_LDB(B1, 0, 1); PG8_SCHED; PG8_LDA(At, 0, 0); PG8_STAGE(PG8_SA(1, 1), a1 + hstep, voffA);
;             PG8_WAIT_V(8); PG8_WAIT_L(0); PG8_BAR; PG8_MMA(0, 0, At, B0); PG8_MMA(0, 1, At, B1); PG8_BAR; PG8_SCHED;
;             PG8_LDA(At, 0, 1); PG8_STAGE(PG8_SB(0, 0), b2, voffB); PG8_STAGE(PG8_SB(0, 1), b2 + hstep, voffB); PG8_STAGE(PG8_SA(0, 0), a2, voffA);
.LBB0_266:
	s_add_u32 s28, s24, 0xfff80080
	s_addc_u32 s29, s25, -1
	s_and_b64 s[26:27], s[26:27], exec
	s_cselect_b32 s29, s17, s29
	s_cselect_b32 s28, s75, s28
	s_cselect_b32 s27, s15, s50
	s_cselect_b32 s26, s85, s23
	s_add_i32 s42, 0, 0x10000
	v_add_u32_e32 v134, s42, v161
	s_add_i32 s43, 0, 0x14000
	ds_read_b128 v[140:143], v134
	ds_read_b128 v[144:147], v134 offset:1024
	ds_read_b128 v[166:169], v134 offset:2048
	ds_read_b128 v[170:173], v134 offset:3072
	v_add_u32_e32 v134, s43, v161
	ds_read_b128 v[174:177], v134
	ds_read_b128 v[186:189], v134 offset:1024
	ds_read_b128 v[190:193], v134 offset:2048
	ds_read_b128 v[194:197], v134 offset:3072
	v_lshl_add_u64 v[134:135], s[24:25], 0, v[156:157]
	s_add_i32 m0, s37, 0xc000
	ds_read_b128 v[198:201], v165
	ds_read_b128 v[202:205], v165 offset:1024
	ds_read_b128 v[206:209], v165 offset:2048
	ds_read_b128 v[210:213], v165 offset:3072
	ds_read_b128 v[214:217], v165 offset:4096
	ds_read_b128 v[218:221], v165 offset:5120
	ds_read_b128 v[222:225], v165 offset:6144
	ds_read_b128 v[226:229], v165 offset:7168
	global_load_lds_dwordx4 v[134:135], off
	v_lshl_add_u64 v[134:135], s[24:25], 0, v[158:159]
	s_add_i32 m0, s37, 0xe000
	s_nop 0
	global_load_lds_dwordx4 v[134:135], off
	s_waitcnt vmcnt(8)
	s_waitcnt lgkmcnt(0)
	s_setprio 1
	s_barrier
	v_mfma_f32_16x16x32_bf16 v[134:137], v[140:143], v[198:201], v[136:139]
	v_mfma_f32_16x16x32_bf16 v[124:127], v[166:169], v[198:201], v[124:127]
	v_mfma_f32_16x16x32_bf16 v[112:115], v[140:143], v[206:209], v[112:115]
	v_mfma_f32_16x16x32_bf16 v[108:111], v[166:169], v[206:209], v[108:111]
	v_mfma_f32_16x16x32_bf16 v[96:99], v[140:143], v[214:217], v[96:99]
	v_mfma_f32_16x16x32_bf16 v[92:95], v[166:169], v[214:217], v[92:95]
	v_mfma_f32_16x16x32_bf16 v[80:83], v[140:143], v[222:225], v[80:83]
	v_mfma_f32_16x16x32_bf16 v[76:79], v[166:169], v[222:225], v[76:79]
	v_mfma_f32_16x16x32_bf16 v[134:137], v[144:147], v[202:205], v[134:137]
	v_mfma_f32_16x16x32_bf16 v[124:127], v[170:173], v[202:205], v[124:127]
	v_mfma_f32_16x16x32_bf16 v[112:115], v[144:147], v[210:213], v[112:115]
	v_mfma_f32_16x16x32_bf16 v[108:111], v[170:173], v[210:213], v[108:111]
	v_mfma_f32_16x16x32_bf16 v[96:99], v[144:147], v[218:221], v[96:99]
	v_mfma_f32_16x16x32_bf16 v[92:95], v[170:173], v[218:221], v[92:95]
	v_mfma_f32_16x16x32_bf16 v[80:83], v[144:147], v[226:229], v[80:83]
	v_mfma_f32_16x16x32_bf16 v[76:79], v[170:173], v[226:229], v[76:79]
	v_mfma_f32_16x16x32_bf16 v[120:123], v[174:177], v[198:201], v[120:123]
	v_mfma_f32_16x16x32_bf16 v[116:119], v[190:193], v[198:201], v[116:119]
	v_mfma_f32_16x16x32_bf16 v[104:107], v[174:177], v[206:209], v[104:107]
	v_mfma_f32_16x16x32_bf16 v[100:103], v[190:193], v[206:209], v[100:103]
	v_mfma_f32_16x16x32_bf16 v[88:91], v[174:177], v[214:217], v[88:91]
	v_mfma_f32_16x16x32_bf16 v[84:87], v[190:193], v[214:217], v[84:87]
	v_mfma_f32_16x16x32_bf16 v[72:75], v[174:177], v[222:225], v[72:75]
	v_mfma_f32_16x16x32_bf16 v[68:71], v[190:193], v[222:225], v[68:71]
	v_mfma_f32_16x16x32_bf16 v[120:123], v[186:189], v[202:205], v[120:123]
	v_mfma_f32_16x16x32_bf16 v[116:119], v[194:197], v[202:205], v[116:119]
	v_mfma_f32_16x16x32_bf16 v[104:107], v[186:189], v[210:213], v[104:107]
	v_mfma_f32_16x16x32_bf16 v[100:103], v[194:197], v[210:213], v[100:103]
	v_mfma_f32_16x16x32_bf16 v[88:91], v[186:189], v[218:221], v[88:91]
	v_mfma_f32_16x16x32_bf16 v[84:87], v[194:197], v[218:221], v[84:87]
	v_mfma_f32_16x16x32_bf16 v[72:75], v[186:189], v[226:229], v[72:75]
	v_mfma_f32_16x16x32_bf16 v[68:71], v[194:197], v[226:229], v[68:71]
	s_setprio 0
	s_barrier
	s_add_i32 s42, s42, s31
	v_lshl_add_u64 v[178:179], s[26:27], 0, v[2:3]
	s_mov_b32 m0, s42
	ds_read_b128 v[198:201], v165 offset:16384
	ds_read_b128 v[202:205], v165 offset:17408
	ds_read_b128 v[206:209], v165 offset:18432
	ds_read_b128 v[210:213], v165 offset:19456
	ds_read_b128 v[214:217], v165 offset:20480
	ds_read_b128 v[218:221], v165 offset:21504
	ds_read_b128 v[222:225], v165 offset:22528
	ds_read_b128 v[226:229], v165 offset:23552
	global_load_lds_dwordx4 v[178:179], off
	s_add_i32 m0, s42, 0x2000
	s_add_u32 s94, s26, 0x80000
	v_lshl_add_u64 v[180:181], s[26:27], 0, v[0:1]
	s_addc_u32 s95, s27, 0
	s_add_i32 s42, s43, s31
	global_load_lds_dwordx4 v[180:181], off
	v_lshl_add_u64 v[138:139], s[94:95], 0, v[2:3]
	s_mov_b32 m0, s42
	v_lshl_add_u64 v[182:183], s[28:29], 0, v[150:151]
	global_load_lds_dwordx4 v[138:139], off
	v_lshl_add_u64 v[138:139], s[94:95], 0, v[0:1]
	s_add_i32 m0, s42, 0x2000
	v_lshl_add_u64 v[230:231], s[28:29], 0, v[148:149]
	global_load_lds_dwordx4 v[138:139], off
	s_mov_b32 m0, s37
	s_nop 0
	global_load_lds_dwordx4 v[182:183], off
	s_mov_b32 m0, s39
	s_nop 0
	global_load_lds_dwordx4 v[230:231], off
	s_waitcnt vmcnt(8)
	s_waitcnt lgkmcnt(0)
	s_setprio 1
	s_barrier
; #define PG8_STAGE(bufoff, gbase, voff) do { _Pragma("unroll") for (int _i = 0; _i < 2; ++_i) \
;         __builtin_amdgcn_global_load_lds((const unsigned*)((const char*)(gbase) + (voff)[_i]), (PG8_LAS unsigned*)(lds + (bufoff) + ldsw + _i * 8192), 16, 0, 0); } while (0)
; #define PG8_LDA(dst, b, h) do { _Pragma("unroll") for (int m = 0; m < 4; ++m) _Pragma("unroll") for (int k = 0; k < 2; ++k) dst[m][k] = *(const PG8_LAS bf16x8*)(lds + PG8_SA(b, h) + aoff + m * 2048 + k * 1024); } while (0)
; #define PG8_LDB(dst, b, h) do { _Pragma("unroll") for (int n = 0; n < 2; ++n) _Pragma("unroll") for (int k = 0; k < 2; ++k) dst[n][k] = *(const PG8_LAS bf16x8*)(lds + PG8_SB(b, h) + boff + n * 2048 + k * 1024); } while (0)
; #define PG8_MMA(ai, bj, At, Bt) do { __builtin_amdgcn_s_setprio(1); _Pragma("unroll") for (int m = 0; m < 4; ++m) _Pragma("unroll") for (int n = 0; n < 2; ++n) _Pragma("unroll") for (int k = 0; k < 2; ++k) \
;         acc[ai][bj][m][n] = __builtin_amdgcn_mfma_f32_16x16x32_bf16(Bt[n][k], At[m][k], acc[ai][bj][m][n], 0, 0, 0); __builtin_amdgcn_s_setprio(0); } while (0)
; #define PG8_WAIT_V(n) asm volatile("s_waitcnt vmcnt(" #n ")" ::: "memory")
; #define PG8_WAIT_L(n) asm volatile("s_waitcnt lgkmcnt(" #n ")" ::: "memory")
; #define PG8_BAR __builtin_amdgcn_s_barrier()
; #define PG8_SCHED __builtin_amdgcn_sched_barrier(0)
; template <class Epi, class Sched, bool ALIGN_EPI = false, bool SP2 = false>
; __device__ __forceinline__ void gemm_phase(PG8_LAS unsigned char* lds, const Gemm g, const Sched& S, const Epi& E, const int tid) {
;     ...
;             PG8_WAIT_V(8); PG8_WAIT_L(0); PG8_BAR; PG8_MMA(1, 0, At, B0); PG8_MMA(1, 1, At, B1); PG8_BAR; PG8_SCHED;
;             PG8_LDB(B0, 1, 0); PG8_LDB(B1, 1, 1); PG8_SCHED; PG8_LDA(At, 1, 0); PG8_STAGE(PG8_SA(0, 1), a2 + hstep, voffA);
;             PG8_WAIT_V(8); PG8_WAIT_L(0); PG8_BAR; PG8_MMA(0, 0, At, B0); PG8_MMA(0, 1, At, B1); PG8_BAR; PG8_SCHED;
	v_mfma_f32_16x16x32_bf16 v[64:67], v[140:143], v[198:201], v[64:67]
	v_mfma_f32_16x16x32_bf16 v[60:63], v[166:169], v[198:201], v[60:63]
	v_mfma_f32_16x16x32_bf16 v[48:51], v[140:143], v[206:209], v[48:51]
	v_mfma_f32_16x16x32_bf16 v[44:47], v[166:169], v[206:209], v[44:47]
	v_mfma_f32_16x16x32_bf16 v[32:35], v[140:143], v[214:217], v[32:35]
	v_mfma_f32_16x16x32_bf16 v[28:31], v[166:169], v[214:217], v[28:31]
	v_mfma_f32_16x16x32_bf16 v[16:19], v[140:143], v[222:225], v[16:19]
	v_mfma_f32_16x16x32_bf16 v[12:15], v[166:169], v[222:225], v[12:15]
	v_mfma_f32_16x16x32_bf16 v[64:67], v[144:147], v[202:205], v[64:67]
	v_mfma_f32_16x16x32_bf16 v[60:63], v[170:173], v[202:205], v[60:63]
	v_mfma_f32_16x16x32_bf16 v[48:51], v[144:147], v[210:213], v[48:51]
	v_mfma_f32_16x16x32_bf16 v[44:47], v[170:173], v[210:213], v[44:47]
	v_mfma_f32_16x16x32_bf16 v[32:35], v[144:147], v[218:221], v[32:35]
	v_mfma_f32_16x16x32_bf16 v[28:31], v[170:173], v[218:221], v[28:31]
	v_mfma_f32_16x16x32_bf16 v[16:19], v[144:147], v[226:229], v[16:19]
	v_mfma_f32_16x16x32_bf16 v[12:15], v[170:173], v[226:229], v[12:15]
	v_mfma_f32_16x16x32_bf16 v[56:59], v[174:177], v[198:201], v[56:59]
	v_mfma_f32_16x16x32_bf16 v[52:55], v[190:193], v[198:201], v[52:55]
	v_mfma_f32_16x16x32_bf16 v[40:43], v[174:177], v[206:209], v[40:43]
	v_mfma_f32_16x16x32_bf16 v[36:39], v[190:193], v[206:209], v[36:39]
	v_mfma_f32_16x16x32_bf16 v[24:27], v[174:177], v[214:217], v[24:27]
	v_mfma_f32_16x16x32_bf16 v[20:23], v[190:193], v[214:217], v[20:23]
	v_mfma_f32_16x16x32_bf16 v[8:11], v[174:177], v[222:225], v[8:11]
	v_mfma_f32_16x16x32_bf16 v[4:7], v[190:193], v[222:225], v[4:7]
	v_mfma_f32_16x16x32_bf16 v[56:59], v[186:189], v[202:205], v[56:59]
	v_mfma_f32_16x16x32_bf16 v[52:55], v[194:197], v[202:205], v[52:55]
	v_mfma_f32_16x16x32_bf16 v[40:43], v[186:189], v[210:213], v[40:43]
	v_mfma_f32_16x16x32_bf16 v[36:39], v[194:197], v[210:213], v[36:39]
	v_mfma_f32_16x16x32_bf16 v[24:27], v[186:189], v[218:221], v[24:27]
	v_mfma_f32_16x16x32_bf16 v[20:23], v[194:197], v[218:221], v[20:23]
	v_mfma_f32_16x16x32_bf16 v[8:11], v[186:189], v[226:229], v[8:11]
	v_mfma_f32_16x16x32_bf16 v[4:7], v[194:197], v[226:229], v[4:7]
	s_setprio 0
	s_barrier
	s_add_i32 s42, 0, 0x18000
	v_add_u32_e32 v138, s42, v161
	s_add_i32 s43, 0, 0x1c000
	ds_read_b128 v[140:143], v138
	ds_read_b128 v[144:147], v138 offset:1024
	ds_read_b128 v[166:169], v138 offset:2048
	ds_read_b128 v[170:173], v138 offset:3072
	v_add_u32_e32 v138, s43, v161
	ds_read_b128 v[174:177], v138
	ds_read_b128 v[186:189], v138 offset:1024
	ds_read_b128 v[190:193], v138 offset:2048
	ds_read_b128 v[194:197], v138 offset:3072
	s_add_u32 s28, s28, 0x80000
	s_addc_u32 s29, s29, 0
	s_mov_b32 m0, s44
	v_lshl_add_u64 v[138:139], s[28:29], 0, v[150:151]
	ds_read_b128 v[198:201], v165 offset:32768
	ds_read_b128 v[202:205], v165 offset:33792
	ds_read_b128 v[206:209], v165 offset:34816
	ds_read_b128 v[210:213], v165 offset:35840
	ds_read_b128 v[214:217], v165 offset:36864
	ds_read_b128 v[218:221], v165 offset:37888
	ds_read_b128 v[222:225], v165 offset:38912
	ds_read_b128 v[226:229], v165 offset:39936
	global_load_lds_dwordx4 v[138:139], off
	v_lshl_add_u64 v[138:139], s[28:29], 0, v[148:149]
	s_mov_b32 m0, s48
	s_nop 0
	global_load_lds_dwordx4 v[138:139], off
	s_waitcnt vmcnt(8)
	s_waitcnt lgkmcnt(0)
	s_setprio 1
	s_barrier
	v_mfma_f32_16x16x32_bf16 v[134:137], v[140:143], v[198:201], v[134:137]
	v_mfma_f32_16x16x32_bf16 v[124:127], v[166:169], v[198:201], v[124:127]
	v_mfma_f32_16x16x32_bf16 v[112:115], v[140:143], v[206:209], v[112:115]
	v_mfma_f32_16x16x32_bf16 v[108:111], v[166:169], v[206:209], v[108:111]
	v_mfma_f32_16x16x32_bf16 v[96:99], v[140:143], v[214:217], v[96:99]
	v_mfma_f32_16x16x32_bf16 v[92:95], v[166:169], v[214:217], v[92:95]
	v_mfma_f32_16x16x32_bf16 v[80:83], v[140:143], v[222:225], v[80:83]
	v_mfma_f32_16x16x32_bf16 v[76:79], v[166:169], v[222:225], v[76:79]
	v_mfma_f32_16x16x32_bf16 v[136:139], v[144:147], v[202:205], v[134:137]
	v_mfma_f32_16x16x32_bf16 v[124:127], v[170:173], v[202:205], v[124:127]
	v_mfma_f32_16x16x32_bf16 v[112:115], v[144:147], v[210:213], v[112:115]
	v_mfma_f32_16x16x32_bf16 v[108:111], v[170:173], v[210:213], v[108:111]
	v_mfma_f32_16x16x32_bf16 v[96:99], v[144:147], v[218:221], v[96:99]
	v_mfma_f32_16x16x32_bf16 v[92:95], v[170:173], v[218:221], v[92:95]
	v_mfma_f32_16x16x32_bf16 v[80:83], v[144:147], v[226:229], v[80:83]
	v_mfma_f32_16x16x32_bf16 v[76:79], v[170:173], v[226:229], v[76:79]
	v_mfma_f32_16x16x32_bf16 v[120:123], v[174:177], v[198:201], v[120:123]
	v_mfma_f32_16x16x32_bf16 v[116:119], v[190:193], v[198:201], v[116:119]
	v_mfma_f32_16x16x32_bf16 v[104:107], v[174:177], v[206:209], v[104:107]
	v_mfma_f32_16x16x32_bf16 v[100:103], v[190:193], v[206:209], v[100:103]
	v_mfma_f32_16x16x32_bf16 v[88:91], v[174:177], v[214:217], v[88:91]
	v_mfma_f32_16x16x32_bf16 v[84:87], v[190:193], v[214:217], v[84:87]
	v_mfma_f32_16x16x32_bf16 v[72:75], v[174:177], v[222:225], v[72:75]
	v_mfma_f32_16x16x32_bf16 v[68:71], v[190:193], v[222:225], v[68:71]
	v_mfma_f32_16x16x32_bf16 v[120:123], v[186:189], v[202:205], v[120:123]
	v_mfma_f32_16x16x32_bf16 v[116:119], v[194:197], v[202:205], v[116:119]
	v_mfma_f32_16x16x32_bf16 v[104:107], v[186:189], v[210:213], v[104:107]
	v_mfma_f32_16x16x32_bf16 v[100:103], v[194:197], v[210:213], v[100:103]
	v_mfma_f32_16x16x32_bf16 v[88:91], v[186:189], v[218:221], v[88:91]
	v_mfma_f32_16x16x32_bf16 v[84:87], v[194:197], v[218:221], v[84:87]
	v_mfma_f32_16x16x32_bf16 v[72:75], v[186:189], v[226:229], v[72:75]
	v_mfma_f32_16x16x32_bf16 v[68:71], v[194:197], v[226:229], v[68:71]
	s_setprio 0
	s_barrier
; #define PG8_STAGE(bufoff, gbase, voff) do { _Pragma("unroll") for (int _i = 0; _i < 2; ++_i) \
;         __builtin_amdgcn_global_load_lds((const unsigned*)((const char*)(gbase) + (voff)[_i]), (PG8_LAS unsigned*)(lds + (bufoff) + ldsw + _i * 8192), 16, 0, 0); } while (0)
; #define PG8_LDA(dst, b, h) do { _Pragma("unroll") for (int m = 0; m < 4; ++m) _Pragma("unroll") for (int k = 0; k < 2; ++k) dst[m][k] = *(const PG8_LAS bf16x8*)(lds + PG8_SA(b, h) + aoff + m * 2048 + k * 1024); } while (0)
; #define PG8_MMA(ai, bj, At, Bt) do { __builtin_amdgcn_s_setprio(1); _Pragma("unroll") for (int m = 0; m < 4; ++m) _Pragma("unroll") for (int n = 0; n < 2; ++n) _Pragma("unroll") for (int k = 0; k < 2; ++k) \
;         acc[ai][bj][m][n] = __builtin_amdgcn_mfma_f32_16x16x32_bf16(Bt[n][k], At[m][k], acc[ai][bj][m][n], 0, 0, 0); __builtin_amdgcn_s_setprio(0); } while (0)
; #define PG8_WAIT_V(n) asm volatile("s_waitcnt vmcnt(" #n ")" ::: "memory")
; #define PG8_WAIT_L(n) asm volatile("s_waitcnt lgkmcnt(" #n ")" ::: "memory")
; #define PG8_BAR __builtin_amdgcn_s_barrier()
; #define PG8_SCHED __builtin_amdgcn_sched_barrier(0)
; template <class Epi, class Sched, bool ALIGN_EPI = false, bool SP2 = false>
; __device__ __forceinline__ void gemm_phase(PG8_LAS unsigned char* lds, const Gemm g, const Sched& S, const Epi& E, const int tid) {
;     ...
;             PG8_LDA(At, 1, 1); PG8_STAGE(PG8_SB(1, 0), b3, voffB); PG8_STAGE(PG8_SB(1, 1), b3 + hstep, voffB); PG8_STAGE(PG8_SA(1, 0), a3, voffA);
;             PG8_WAIT_V(8); PG8_WAIT_L(0); PG8_BAR; PG8_MMA(1, 0, At, B0); PG8_MMA(1, 1, At, B1); PG8_BAR; PG8_SCHED;
	s_add_i32 s28, s42, s31
	v_lshl_add_u64 v[134:135], v[178:179], 0, s[46:47]
	s_mov_b32 m0, s28
	ds_read_b128 v[198:201], v165 offset:49152
	ds_read_b128 v[202:205], v165 offset:50176
	ds_read_b128 v[206:209], v165 offset:51200
	ds_read_b128 v[210:213], v165 offset:52224
	ds_read_b128 v[214:217], v165 offset:53248
	ds_read_b128 v[218:221], v165 offset:54272
	ds_read_b128 v[222:225], v165 offset:55296
	ds_read_b128 v[226:229], v165 offset:56320
	global_load_lds_dwordx4 v[134:135], off
	s_add_i32 m0, s28, 0x2000
	s_add_u32 s26, s26, 0x80080
	v_lshl_add_u64 v[134:135], v[180:181], 0, s[46:47]
	s_addc_u32 s27, s27, 0
	s_add_i32 s28, s43, s31
	global_load_lds_dwordx4 v[134:135], off
	v_lshl_add_u64 v[134:135], s[26:27], 0, v[2:3]
	s_mov_b32 m0, s28
	s_nop 0
	global_load_lds_dwordx4 v[134:135], off
	v_lshl_add_u64 v[134:135], s[26:27], 0, v[0:1]
	s_add_i32 m0, s28, 0x2000
	s_nop 0
	global_load_lds_dwordx4 v[134:135], off
	v_lshl_add_u64 v[134:135], v[182:183], 0, s[46:47]
	s_mov_b32 m0, s52
	s_nop 0
	global_load_lds_dwordx4 v[134:135], off
	v_lshl_add_u64 v[134:135], v[230:231], 0, s[46:47]
	s_mov_b32 m0, s53
	s_nop 0
	global_load_lds_dwordx4 v[134:135], off
	s_waitcnt vmcnt(8)
	s_waitcnt lgkmcnt(0)
	s_setprio 1
	s_barrier
	v_mfma_f32_16x16x32_bf16 v[64:67], v[140:143], v[198:201], v[64:67]
	v_mfma_f32_16x16x32_bf16 v[60:63], v[166:169], v[198:201], v[60:63]
	v_mfma_f32_16x16x32_bf16 v[48:51], v[140:143], v[206:209], v[48:51]
	v_mfma_f32_16x16x32_bf16 v[44:47], v[166:169], v[206:209], v[44:47]
	v_mfma_f32_16x16x32_bf16 v[32:35], v[140:143], v[214:217], v[32:35]
	v_mfma_f32_16x16x32_bf16 v[28:31], v[166:169], v[214:217], v[28:31]
	v_mfma_f32_16x16x32_bf16 v[16:19], v[140:143], v[222:225], v[16:19]
	v_mfma_f32_16x16x32_bf16 v[12:15], v[166:169], v[222:225], v[12:15]
	v_mfma_f32_16x16x32_bf16 v[64:67], v[144:147], v[202:205], v[64:67]
	v_mfma_f32_16x16x32_bf16 v[60:63], v[170:173], v[202:205], v[60:63]
	v_mfma_f32_16x16x32_bf16 v[48:51], v[144:147], v[210:213], v[48:51]
	v_mfma_f32_16x16x32_bf16 v[44:47], v[170:173], v[210:213], v[44:47]
	v_mfma_f32_16x16x32_bf16 v[32:35], v[144:147], v[218:221], v[32:35]
	v_mfma_f32_16x16x32_bf16 v[28:31], v[170:173], v[218:221], v[28:31]
	v_mfma_f32_16x16x32_bf16 v[16:19], v[144:147], v[226:229], v[16:19]
	v_mfma_f32_16x16x32_bf16 v[12:15], v[170:173], v[226:229], v[12:15]
	v_mfma_f32_16x16x32_bf16 v[56:59], v[174:177], v[198:201], v[56:59]
	v_mfma_f32_16x16x32_bf16 v[52:55], v[190:193], v[198:201], v[52:55]
	v_mfma_f32_16x16x32_bf16 v[40:43], v[174:177], v[206:209], v[40:43]
	v_mfma_f32_16x16x32_bf16 v[36:39], v[190:193], v[206:209], v[36:39]
	v_mfma_f32_16x16x32_bf16 v[24:27], v[174:177], v[214:217], v[24:27]
	v_mfma_f32_16x16x32_bf16 v[20:23], v[190:193], v[214:217], v[20:23]
	v_mfma_f32_16x16x32_bf16 v[8:11], v[174:177], v[222:225], v[8:11]
	v_mfma_f32_16x16x32_bf16 v[4:7], v[190:193], v[222:225], v[4:7]
	v_mfma_f32_16x16x32_bf16 v[56:59], v[186:189], v[202:205], v[56:59]
	v_mfma_f32_16x16x32_bf16 v[52:55], v[194:197], v[202:205], v[52:55]
	v_mfma_f32_16x16x32_bf16 v[40:43], v[186:189], v[210:213], v[40:43]
	v_mfma_f32_16x16x32_bf16 v[36:39], v[194:197], v[210:213], v[36:39]
	v_mfma_f32_16x16x32_bf16 v[24:27], v[186:189], v[218:221], v[24:27]
	v_mfma_f32_16x16x32_bf16 v[20:23], v[194:197], v[218:221], v[20:23]
	v_mfma_f32_16x16x32_bf16 v[8:11], v[186:189], v[226:229], v[8:11]
	v_mfma_f32_16x16x32_bf16 v[4:7], v[194:197], v[226:229], v[4:7]
	s_setprio 0
	s_barrier
	s_add_i32 s51, s51, 2
	s_add_u32 s24, s24, 0x100
	s_addc_u32 s25, s25, 0
	s_add_u32 s23, s23, 0x100
	s_addc_u32 s50, s50, 0
	s_cmp_gt_u32 s51, 29
	s_cbranch_scc1 .LBB0_269
